# scan inner loop hand-rescheduled (software-pipelined LDS operand refills, DPP chains separated by VALU ops)
# baseline (speedup 1.0000x reference)
; DI float oct_sum(float v) { v += dpp_f<0xB1>(v); v += dpp_f<0x4E>(v); v += dpp_f<0x141>(v); return v; }
; DI void scan_item(const Params& p, int b, int h, int half, char* smem, unsigned* pgen, unsigned kp) {
;     ...
; #pragma unroll 1
;     for (int sg = 0; sg < SC; sg += 4) {
;       float yy[4];
; #pragma unroll
;       for (int s4 = 0; s4 < 4; ++s4) {
;         const int s = sg + s4;
;         const f32x2* a2 = (const f32x2*)(Al + s * 64 + cg * 8);
;         const f32x2* w2 = (const f32x2*)(Wl + s * 64 + cg * 8);
;         const f32x2* b2 = (const f32x2*)(Bl + s * 64 + cg * 8);
;         const f32x2* k2 = (const f32x2*)(Kl + s * 64 + cg * 8);
;         const f32x2* r2 = (const f32x2*)(Rl + s * 64 + cg * 8);
;         f32x2 o[20];
; #pragma unroll
;         for (int i = 0; i < 4; ++i) { o[i] = a2[i]; o[4 + i] = w2[i]; o[8 + i] = b2[i]; o[12 + i] = k2[i]; o[16 + i] = r2[i]; }
;         const float vr = Vl[s * 64 + 32 * half + rp];
;         f32x2 p0 = St[0] * o[0], p1 = St[1] * o[1];
;         p0 = __builtin_elementwise_fma(St[2], o[2], p0); p1 = __builtin_elementwise_fma(St[3], o[3], p1);
;         const float sa = oct_sum((p0.x + p0.y) + (p1.x + p1.y));
;         const f32x2 sv = {sa, sa}, vv = {vr, vr};
;         f32x2 y0 = {0.f, 0.f}, y1 = {0.f, 0.f};
; #pragma unroll
;         for (int i = 0; i < 4; i += 2) {
;           St[i] = __builtin_elementwise_fma(St[i], o[4 + i], __builtin_elementwise_fma(sv, o[8 + i], vv * o[12 + i]));
;           St[i + 1] = __builtin_elementwise_fma(St[i + 1], o[5 + i], __builtin_elementwise_fma(sv, o[9 + i], vv * o[13 + i]));
;           y0 = __builtin_elementwise_fma(St[i], o[16 + i], y0);
;           y1 = __builtin_elementwise_fma(St[i + 1], o[17 + i], y1);
;         }
;         yy[s4] = oct_sum((y0.x + y0.y) + (y1.x + y1.y));
;       }
;       if (cg == 0) {
; #pragma unroll
;         for (int s4 = 0; s4 < 4; ++s4) Yl[(sg + s4) * 32 + rp] = yy[s4];
;       }
;     }
.LBB0_701:
	s_mov_b32 s26, -4
	v_mov_b32_e32 v0, v214
	v_mov_b32_e32 v161, v160
	v_mov_b32_e32 v162, v225
	ds_read_b128 v[34:37], v0 offset:16384
	ds_read_b128 v[38:41], v0 offset:16400
	ds_read_b128 v[68:71], v0 offset:8192
	ds_read_b128 v[150:153], v0 offset:8208
	ds_read2st64_b32 v[158:159], v161 offset0:0 offset1:1
	ds_read_b128 v[50:53], v0 offset:20480
	ds_read_b128 v[54:57], v0 offset:20496
	ds_read_b128 v[42:45], v0 offset:4096
	ds_read_b128 v[46:49], v0 offset:4112
	ds_read_b128 v[154:157], v0 offset:0
	ds_read_b128 v[246:249], v0 offset:16
	ds_read_b128 v[200:203], v0 offset:16640
	ds_read_b128 v[230:233], v0 offset:16656
	s_waitcnt lgkmcnt(11)
	v_pk_mul_f32 v[34:35], v[66:67], v[34:35]
	v_pk_mul_f32 v[36:37], v[64:65], v[36:37]
	v_pk_fma_f32 v[34:35], v[62:63], v[38:39], v[34:35]
	v_pk_fma_f32 v[36:37], v[60:61], v[40:41], v[36:37]
	v_add_f32_e32 v198, v34, v35
	v_add_f32_e32 v199, v36, v37
	v_add_f32_e32 v198, v198, v199
	s_waitcnt lgkmcnt(8)
	v_pk_mul_f32 v[58:59], v[68:69], v[158:159] op_sel_hi:[1,0]
	v_pk_mul_f32 v[72:73], v[70:71], v[158:159] op_sel_hi:[1,0]
	ds_read_b128 v[68:71], v0 offset:8448
	v_add_f32_dpp v198, v198, v198 quad_perm:[1,0,3,2] row_mask:0xf bank_mask:0xf bound_ctrl:1
	s_nop 0
	v_pk_mul_f32 v[212:213], v[150:151], v[158:159] op_sel_hi:[1,0]
	v_add_f32_dpp v198, v198, v198 quad_perm:[2,3,0,1] row_mask:0xf bank_mask:0xf bound_ctrl:1
	s_nop 0
	v_pk_mul_f32 v[250:251], v[152:153], v[158:159] op_sel_hi:[1,0]
	ds_read_b128 v[150:153], v0 offset:8464
	v_add_f32_dpp v198, v198, v198 row_half_mirror row_mask:0xf bank_mask:0xf bound_ctrl:1
	s_waitcnt lgkmcnt(8)
	v_pk_fma_f32 v[58:59], v[198:199], v[50:51], v[58:59] op_sel_hi:[0,1,1]
	v_pk_fma_f32 v[72:73], v[198:199], v[52:53], v[72:73] op_sel_hi:[0,1,1]
	s_waitcnt lgkmcnt(6)
	v_pk_fma_f32 v[66:67], v[66:67], v[42:43], v[58:59]
	v_pk_fma_f32 v[64:65], v[64:65], v[44:45], v[72:73]
	v_pk_fma_f32 v[212:213], v[198:199], v[54:55], v[212:213] op_sel_hi:[0,1,1]
	v_pk_fma_f32 v[250:251], v[198:199], v[56:57], v[250:251] op_sel_hi:[0,1,1]
	v_pk_fma_f32 v[62:63], v[62:63], v[46:47], v[212:213]
	v_pk_fma_f32 v[60:61], v[60:61], v[48:49], v[250:251]
	ds_read_b128 v[50:53], v0 offset:20736
	ds_read_b128 v[54:57], v0 offset:20752
	ds_read_b128 v[42:45], v0 offset:4352
	ds_read_b128 v[46:49], v0 offset:4368
	s_waitcnt lgkmcnt(8)
	v_pk_fma_f32 v[58:59], v[66:67], v[154:155], 0 op_sel_hi:[1,1,0]
	v_pk_fma_f32 v[72:73], v[64:65], v[156:157], 0 op_sel_hi:[1,1,0]
	v_pk_fma_f32 v[58:59], v[62:63], v[246:247], v[58:59]
	v_pk_fma_f32 v[72:73], v[60:61], v[248:249], v[72:73]
	ds_read_b128 v[154:157], v0 offset:256
	ds_read_b128 v[246:249], v0 offset:272
	v_add_f32_e32 v207, v58, v59
	v_add_f32_e32 v209, v72, v73
	ds_read_b128 v[34:37], v0 offset:16896
	ds_read_b128 v[38:41], v0 offset:16912
	s_waitcnt lgkmcnt(10)
	v_pk_mul_f32 v[200:201], v[66:67], v[200:201]
	v_pk_mul_f32 v[202:203], v[64:65], v[202:203]
	v_pk_fma_f32 v[200:201], v[62:63], v[230:231], v[200:201]
	v_pk_fma_f32 v[202:203], v[60:61], v[232:233], v[202:203]
	v_add_f32_e32 v198, v200, v201
	v_add_f32_e32 v199, v202, v203
	v_add_f32_e32 v207, v207, v209
	v_add_f32_e32 v198, v198, v199
	s_waitcnt lgkmcnt(8)
	v_pk_mul_f32 v[58:59], v[68:69], v[158:159] op_sel:[0,1] op_sel_hi:[1,1]
	v_pk_mul_f32 v[72:73], v[70:71], v[158:159] op_sel:[0,1] op_sel_hi:[1,1]
	ds_read_b128 v[68:71], v0 offset:8704
	v_add_f32_dpp v198, v198, v198 quad_perm:[1,0,3,2] row_mask:0xf bank_mask:0xf bound_ctrl:1
	v_add_f32_dpp v207, v207, v207 quad_perm:[1,0,3,2] row_mask:0xf bank_mask:0xf bound_ctrl:1
	v_pk_mul_f32 v[212:213], v[150:151], v[158:159] op_sel:[0,1] op_sel_hi:[1,1]
	v_add_f32_dpp v198, v198, v198 quad_perm:[2,3,0,1] row_mask:0xf bank_mask:0xf bound_ctrl:1
	v_add_f32_dpp v207, v207, v207 quad_perm:[2,3,0,1] row_mask:0xf bank_mask:0xf bound_ctrl:1
	v_pk_mul_f32 v[250:251], v[152:153], v[158:159] op_sel:[0,1] op_sel_hi:[1,1]
	ds_read_b128 v[150:153], v0 offset:8720
	v_add_f32_dpp v198, v198, v198 row_half_mirror row_mask:0xf bank_mask:0xf bound_ctrl:1
	v_add_f32_dpp v163, v207, v207 row_half_mirror row_mask:0xf bank_mask:0xf bound_ctrl:1
	ds_read2st64_b32 v[158:159], v161 offset0:2 offset1:3
	ds_write_b32 v162, v163 offset:0
	s_waitcnt lgkmcnt(9)
	v_pk_fma_f32 v[58:59], v[198:199], v[50:51], v[58:59] op_sel_hi:[0,1,1]
	v_pk_fma_f32 v[72:73], v[198:199], v[52:53], v[72:73] op_sel_hi:[0,1,1]
	s_waitcnt lgkmcnt(7)
	v_pk_fma_f32 v[66:67], v[66:67], v[42:43], v[58:59]
	v_pk_fma_f32 v[64:65], v[64:65], v[44:45], v[72:73]
	v_pk_fma_f32 v[212:213], v[198:199], v[54:55], v[212:213] op_sel_hi:[0,1,1]
	v_pk_fma_f32 v[250:251], v[198:199], v[56:57], v[250:251] op_sel_hi:[0,1,1]
	v_pk_fma_f32 v[62:63], v[62:63], v[46:47], v[212:213]
	v_pk_fma_f32 v[60:61], v[60:61], v[48:49], v[250:251]
	ds_read_b128 v[50:53], v0 offset:20992
	ds_read_b128 v[54:57], v0 offset:21008
	ds_read_b128 v[42:45], v0 offset:4608
	ds_read_b128 v[46:49], v0 offset:4624
	s_waitcnt lgkmcnt(9)
	v_pk_fma_f32 v[58:59], v[66:67], v[154:155], 0 op_sel_hi:[1,1,0]
	v_pk_fma_f32 v[72:73], v[64:65], v[156:157], 0 op_sel_hi:[1,1,0]
	v_pk_fma_f32 v[58:59], v[62:63], v[246:247], v[58:59]
	v_pk_fma_f32 v[72:73], v[60:61], v[248:249], v[72:73]
	ds_read_b128 v[154:157], v0 offset:512
	ds_read_b128 v[246:249], v0 offset:528
	v_add_f32_e32 v207, v58, v59
	v_add_f32_e32 v209, v72, v73
	ds_read_b128 v[200:203], v0 offset:17152
	ds_read_b128 v[230:233], v0 offset:17168
	s_waitcnt lgkmcnt(11)
	v_pk_mul_f32 v[34:35], v[66:67], v[34:35]
	v_pk_mul_f32 v[36:37], v[64:65], v[36:37]
	v_pk_fma_f32 v[34:35], v[62:63], v[38:39], v[34:35]
	v_pk_fma_f32 v[36:37], v[60:61], v[40:41], v[36:37]
	v_add_f32_e32 v198, v34, v35
	v_add_f32_e32 v199, v36, v37
	v_add_f32_e32 v207, v207, v209
	v_add_f32_e32 v198, v198, v199
	s_waitcnt lgkmcnt(8)
; DI float oct_sum(float v) { v += dpp_f<0xB1>(v); v += dpp_f<0x4E>(v); v += dpp_f<0x141>(v); return v; }
; DI void scan_item(const Params& p, int b, int h, int half, char* smem, unsigned* pgen, unsigned kp) {
;     ...
; #pragma unroll 1
;     for (int sg = 0; sg < SC; sg += 4) {
;       float yy[4];
; #pragma unroll
;       for (int s4 = 0; s4 < 4; ++s4) {
;         const int s = sg + s4;
;         const f32x2* a2 = (const f32x2*)(Al + s * 64 + cg * 8);
;         const f32x2* w2 = (const f32x2*)(Wl + s * 64 + cg * 8);
;         const f32x2* b2 = (const f32x2*)(Bl + s * 64 + cg * 8);
;         const f32x2* k2 = (const f32x2*)(Kl + s * 64 + cg * 8);
;         const f32x2* r2 = (const f32x2*)(Rl + s * 64 + cg * 8);
;         f32x2 o[20];
; #pragma unroll
;         for (int i = 0; i < 4; ++i) { o[i] = a2[i]; o[4 + i] = w2[i]; o[8 + i] = b2[i]; o[12 + i] = k2[i]; o[16 + i] = r2[i]; }
;         const float vr = Vl[s * 64 + 32 * half + rp];
;         f32x2 p0 = St[0] * o[0], p1 = St[1] * o[1];
;         p0 = __builtin_elementwise_fma(St[2], o[2], p0); p1 = __builtin_elementwise_fma(St[3], o[3], p1);
;         const float sa = oct_sum((p0.x + p0.y) + (p1.x + p1.y));
;         const f32x2 sv = {sa, sa}, vv = {vr, vr};
;         f32x2 y0 = {0.f, 0.f}, y1 = {0.f, 0.f};
; #pragma unroll
;         for (int i = 0; i < 4; i += 2) {
;           St[i] = __builtin_elementwise_fma(St[i], o[4 + i], __builtin_elementwise_fma(sv, o[8 + i], vv * o[12 + i]));
;           St[i + 1] = __builtin_elementwise_fma(St[i + 1], o[5 + i], __builtin_elementwise_fma(sv, o[9 + i], vv * o[13 + i]));
;           y0 = __builtin_elementwise_fma(St[i], o[16 + i], y0);
;           y1 = __builtin_elementwise_fma(St[i + 1], o[17 + i], y1);
;         }
;         yy[s4] = oct_sum((y0.x + y0.y) + (y1.x + y1.y));
;       }
;       if (cg == 0) {
; #pragma unroll
;         for (int s4 = 0; s4 < 4; ++s4) Yl[(sg + s4) * 32 + rp] = yy[s4];
;       }
;     }
	v_pk_mul_f32 v[58:59], v[68:69], v[158:159] op_sel_hi:[1,0]
	v_pk_mul_f32 v[72:73], v[70:71], v[158:159] op_sel_hi:[1,0]
	ds_read_b128 v[68:71], v0 offset:8960
	v_add_f32_dpp v198, v198, v198 quad_perm:[1,0,3,2] row_mask:0xf bank_mask:0xf bound_ctrl:1
	v_add_f32_dpp v207, v207, v207 quad_perm:[1,0,3,2] row_mask:0xf bank_mask:0xf bound_ctrl:1
	v_pk_mul_f32 v[212:213], v[150:151], v[158:159] op_sel_hi:[1,0]
	v_add_f32_dpp v198, v198, v198 quad_perm:[2,3,0,1] row_mask:0xf bank_mask:0xf bound_ctrl:1
	v_add_f32_dpp v207, v207, v207 quad_perm:[2,3,0,1] row_mask:0xf bank_mask:0xf bound_ctrl:1
	v_pk_mul_f32 v[250:251], v[152:153], v[158:159] op_sel_hi:[1,0]
	ds_read_b128 v[150:153], v0 offset:8976
	v_add_f32_dpp v198, v198, v198 row_half_mirror row_mask:0xf bank_mask:0xf bound_ctrl:1
	v_add_f32_dpp v205, v207, v207 row_half_mirror row_mask:0xf bank_mask:0xf bound_ctrl:1
	ds_write_b32 v162, v205 offset:128
	s_waitcnt lgkmcnt(8)
	v_pk_fma_f32 v[58:59], v[198:199], v[50:51], v[58:59] op_sel_hi:[0,1,1]
	v_pk_fma_f32 v[72:73], v[198:199], v[52:53], v[72:73] op_sel_hi:[0,1,1]
	s_waitcnt lgkmcnt(6)
	v_pk_fma_f32 v[66:67], v[66:67], v[42:43], v[58:59]
	v_pk_fma_f32 v[64:65], v[64:65], v[44:45], v[72:73]
	v_pk_fma_f32 v[212:213], v[198:199], v[54:55], v[212:213] op_sel_hi:[0,1,1]
	v_pk_fma_f32 v[250:251], v[198:199], v[56:57], v[250:251] op_sel_hi:[0,1,1]
	v_pk_fma_f32 v[62:63], v[62:63], v[46:47], v[212:213]
	v_pk_fma_f32 v[60:61], v[60:61], v[48:49], v[250:251]
	ds_read_b128 v[50:53], v0 offset:21248
	ds_read_b128 v[54:57], v0 offset:21264
	ds_read_b128 v[42:45], v0 offset:4864
	ds_read_b128 v[46:49], v0 offset:4880
	s_waitcnt lgkmcnt(8)
	v_pk_fma_f32 v[58:59], v[66:67], v[154:155], 0 op_sel_hi:[1,1,0]
	v_pk_fma_f32 v[72:73], v[64:65], v[156:157], 0 op_sel_hi:[1,1,0]
	v_pk_fma_f32 v[58:59], v[62:63], v[246:247], v[58:59]
	v_pk_fma_f32 v[72:73], v[60:61], v[248:249], v[72:73]
	ds_read_b128 v[154:157], v0 offset:768
	ds_read_b128 v[246:249], v0 offset:784
	v_add_f32_e32 v207, v58, v59
	v_add_f32_e32 v209, v72, v73
	ds_read_b128 v[34:37], v0 offset:17408
	ds_read_b128 v[38:41], v0 offset:17424
	s_waitcnt lgkmcnt(10)
	v_pk_mul_f32 v[200:201], v[66:67], v[200:201]
	v_pk_mul_f32 v[202:203], v[64:65], v[202:203]
	v_pk_fma_f32 v[200:201], v[62:63], v[230:231], v[200:201]
	v_pk_fma_f32 v[202:203], v[60:61], v[232:233], v[202:203]
	v_add_f32_e32 v198, v200, v201
	v_add_f32_e32 v199, v202, v203
	v_add_f32_e32 v207, v207, v209
	v_add_f32_e32 v198, v198, v199
	s_waitcnt lgkmcnt(8)
	v_pk_mul_f32 v[58:59], v[68:69], v[158:159] op_sel:[0,1] op_sel_hi:[1,1]
	v_pk_mul_f32 v[72:73], v[70:71], v[158:159] op_sel:[0,1] op_sel_hi:[1,1]
	ds_read_b128 v[68:71], v0 offset:9216
	v_add_f32_dpp v198, v198, v198 quad_perm:[1,0,3,2] row_mask:0xf bank_mask:0xf bound_ctrl:1
	v_add_f32_dpp v207, v207, v207 quad_perm:[1,0,3,2] row_mask:0xf bank_mask:0xf bound_ctrl:1
	v_pk_mul_f32 v[212:213], v[150:151], v[158:159] op_sel:[0,1] op_sel_hi:[1,1]
	v_add_f32_dpp v198, v198, v198 quad_perm:[2,3,0,1] row_mask:0xf bank_mask:0xf bound_ctrl:1
	v_add_f32_dpp v207, v207, v207 quad_perm:[2,3,0,1] row_mask:0xf bank_mask:0xf bound_ctrl:1
	v_pk_mul_f32 v[250:251], v[152:153], v[158:159] op_sel:[0,1] op_sel_hi:[1,1]
	ds_read_b128 v[150:153], v0 offset:9232
	v_add_f32_dpp v198, v198, v198 row_half_mirror row_mask:0xf bank_mask:0xf bound_ctrl:1
	v_add_f32_dpp v163, v207, v207 row_half_mirror row_mask:0xf bank_mask:0xf bound_ctrl:1
	ds_read2st64_b32 v[158:159], v161 offset0:4 offset1:5
	ds_write_b32 v162, v163 offset:256
	s_waitcnt lgkmcnt(9)
	v_pk_fma_f32 v[58:59], v[198:199], v[50:51], v[58:59] op_sel_hi:[0,1,1]
	v_pk_fma_f32 v[72:73], v[198:199], v[52:53], v[72:73] op_sel_hi:[0,1,1]
	s_waitcnt lgkmcnt(7)
	v_pk_fma_f32 v[66:67], v[66:67], v[42:43], v[58:59]
	v_pk_fma_f32 v[64:65], v[64:65], v[44:45], v[72:73]
	v_pk_fma_f32 v[212:213], v[198:199], v[54:55], v[212:213] op_sel_hi:[0,1,1]
	v_pk_fma_f32 v[250:251], v[198:199], v[56:57], v[250:251] op_sel_hi:[0,1,1]
	v_pk_fma_f32 v[62:63], v[62:63], v[46:47], v[212:213]
	v_pk_fma_f32 v[60:61], v[60:61], v[48:49], v[250:251]
	ds_read_b128 v[50:53], v0 offset:21504
	ds_read_b128 v[54:57], v0 offset:21520
	ds_read_b128 v[42:45], v0 offset:5120
	ds_read_b128 v[46:49], v0 offset:5136
	s_waitcnt lgkmcnt(9)
	v_pk_fma_f32 v[58:59], v[66:67], v[154:155], 0 op_sel_hi:[1,1,0]
	v_pk_fma_f32 v[72:73], v[64:65], v[156:157], 0 op_sel_hi:[1,1,0]
	v_pk_fma_f32 v[58:59], v[62:63], v[246:247], v[58:59]
	v_pk_fma_f32 v[72:73], v[60:61], v[248:249], v[72:73]
	ds_read_b128 v[154:157], v0 offset:1024
	ds_read_b128 v[246:249], v0 offset:1040
	v_add_f32_e32 v207, v58, v59
	v_add_f32_e32 v209, v72, v73
	ds_read_b128 v[200:203], v0 offset:17664
	ds_read_b128 v[230:233], v0 offset:17680
	s_waitcnt lgkmcnt(11)
	v_pk_mul_f32 v[34:35], v[66:67], v[34:35]
	v_pk_mul_f32 v[36:37], v[64:65], v[36:37]
	v_pk_fma_f32 v[34:35], v[62:63], v[38:39], v[34:35]
	v_pk_fma_f32 v[36:37], v[60:61], v[40:41], v[36:37]
	v_add_f32_e32 v198, v34, v35
	v_add_f32_e32 v199, v36, v37
	v_add_f32_e32 v207, v207, v209
	v_add_f32_e32 v198, v198, v199
	s_waitcnt lgkmcnt(8)
	v_pk_mul_f32 v[58:59], v[68:69], v[158:159] op_sel_hi:[1,0]
	v_pk_mul_f32 v[72:73], v[70:71], v[158:159] op_sel_hi:[1,0]
	ds_read_b128 v[68:71], v0 offset:9472
	v_add_f32_dpp v198, v198, v198 quad_perm:[1,0,3,2] row_mask:0xf bank_mask:0xf bound_ctrl:1
	v_add_f32_dpp v207, v207, v207 quad_perm:[1,0,3,2] row_mask:0xf bank_mask:0xf bound_ctrl:1
	v_pk_mul_f32 v[212:213], v[150:151], v[158:159] op_sel_hi:[1,0]
	v_add_f32_dpp v198, v198, v198 quad_perm:[2,3,0,1] row_mask:0xf bank_mask:0xf bound_ctrl:1
	v_add_f32_dpp v207, v207, v207 quad_perm:[2,3,0,1] row_mask:0xf bank_mask:0xf bound_ctrl:1
	v_pk_mul_f32 v[250:251], v[152:153], v[158:159] op_sel_hi:[1,0]
	ds_read_b128 v[150:153], v0 offset:9488
	v_add_f32_dpp v198, v198, v198 row_half_mirror row_mask:0xf bank_mask:0xf bound_ctrl:1
	v_add_f32_dpp v205, v207, v207 row_half_mirror row_mask:0xf bank_mask:0xf bound_ctrl:1
	ds_write_b32 v162, v205 offset:384
	s_waitcnt lgkmcnt(8)
; DI float oct_sum(float v) { v += dpp_f<0xB1>(v); v += dpp_f<0x4E>(v); v += dpp_f<0x141>(v); return v; }
; DI void scan_item(const Params& p, int b, int h, int half, char* smem, unsigned* pgen, unsigned kp) {
;     ...
; #pragma unroll 1
;     for (int sg = 0; sg < SC; sg += 4) {
;       float yy[4];
; #pragma unroll
;       for (int s4 = 0; s4 < 4; ++s4) {
;         const int s = sg + s4;
;         const f32x2* a2 = (const f32x2*)(Al + s * 64 + cg * 8);
;         const f32x2* w2 = (const f32x2*)(Wl + s * 64 + cg * 8);
;         const f32x2* b2 = (const f32x2*)(Bl + s * 64 + cg * 8);
;         const f32x2* k2 = (const f32x2*)(Kl + s * 64 + cg * 8);
;         const f32x2* r2 = (const f32x2*)(Rl + s * 64 + cg * 8);
;         f32x2 o[20];
; #pragma unroll
;         for (int i = 0; i < 4; ++i) { o[i] = a2[i]; o[4 + i] = w2[i]; o[8 + i] = b2[i]; o[12 + i] = k2[i]; o[16 + i] = r2[i]; }
;         const float vr = Vl[s * 64 + 32 * half + rp];
;         f32x2 p0 = St[0] * o[0], p1 = St[1] * o[1];
;         p0 = __builtin_elementwise_fma(St[2], o[2], p0); p1 = __builtin_elementwise_fma(St[3], o[3], p1);
;         const float sa = oct_sum((p0.x + p0.y) + (p1.x + p1.y));
;         const f32x2 sv = {sa, sa}, vv = {vr, vr};
;         f32x2 y0 = {0.f, 0.f}, y1 = {0.f, 0.f};
; #pragma unroll
;         for (int i = 0; i < 4; i += 2) {
;           St[i] = __builtin_elementwise_fma(St[i], o[4 + i], __builtin_elementwise_fma(sv, o[8 + i], vv * o[12 + i]));
;           St[i + 1] = __builtin_elementwise_fma(St[i + 1], o[5 + i], __builtin_elementwise_fma(sv, o[9 + i], vv * o[13 + i]));
;           y0 = __builtin_elementwise_fma(St[i], o[16 + i], y0);
;           y1 = __builtin_elementwise_fma(St[i + 1], o[17 + i], y1);
;         }
;         yy[s4] = oct_sum((y0.x + y0.y) + (y1.x + y1.y));
;       }
;       if (cg == 0) {
; #pragma unroll
;         for (int s4 = 0; s4 < 4; ++s4) Yl[(sg + s4) * 32 + rp] = yy[s4];
;       }
;     }
	v_pk_fma_f32 v[58:59], v[198:199], v[50:51], v[58:59] op_sel_hi:[0,1,1]
	v_pk_fma_f32 v[72:73], v[198:199], v[52:53], v[72:73] op_sel_hi:[0,1,1]
	s_waitcnt lgkmcnt(6)
	v_pk_fma_f32 v[66:67], v[66:67], v[42:43], v[58:59]
	v_pk_fma_f32 v[64:65], v[64:65], v[44:45], v[72:73]
	v_pk_fma_f32 v[212:213], v[198:199], v[54:55], v[212:213] op_sel_hi:[0,1,1]
	v_pk_fma_f32 v[250:251], v[198:199], v[56:57], v[250:251] op_sel_hi:[0,1,1]
	v_pk_fma_f32 v[62:63], v[62:63], v[46:47], v[212:213]
	v_pk_fma_f32 v[60:61], v[60:61], v[48:49], v[250:251]
	ds_read_b128 v[50:53], v0 offset:21760
	ds_read_b128 v[54:57], v0 offset:21776
	ds_read_b128 v[42:45], v0 offset:5376
	ds_read_b128 v[46:49], v0 offset:5392
	s_waitcnt lgkmcnt(8)
	v_pk_fma_f32 v[58:59], v[66:67], v[154:155], 0 op_sel_hi:[1,1,0]
	v_pk_fma_f32 v[72:73], v[64:65], v[156:157], 0 op_sel_hi:[1,1,0]
	v_pk_fma_f32 v[58:59], v[62:63], v[246:247], v[58:59]
	v_pk_fma_f32 v[72:73], v[60:61], v[248:249], v[72:73]
	ds_read_b128 v[154:157], v0 offset:1280
	ds_read_b128 v[246:249], v0 offset:1296
	v_add_f32_e32 v207, v58, v59
	v_add_f32_e32 v209, v72, v73
	ds_read_b128 v[34:37], v0 offset:17920
	ds_read_b128 v[38:41], v0 offset:17936
	s_waitcnt lgkmcnt(10)
	v_pk_mul_f32 v[200:201], v[66:67], v[200:201]
	v_pk_mul_f32 v[202:203], v[64:65], v[202:203]
	v_pk_fma_f32 v[200:201], v[62:63], v[230:231], v[200:201]
	v_pk_fma_f32 v[202:203], v[60:61], v[232:233], v[202:203]
	v_add_f32_e32 v198, v200, v201
	v_add_f32_e32 v199, v202, v203
	v_add_f32_e32 v207, v207, v209
	v_add_f32_e32 v198, v198, v199
	s_waitcnt lgkmcnt(8)
	v_pk_mul_f32 v[58:59], v[68:69], v[158:159] op_sel:[0,1] op_sel_hi:[1,1]
	v_pk_mul_f32 v[72:73], v[70:71], v[158:159] op_sel:[0,1] op_sel_hi:[1,1]
	ds_read_b128 v[68:71], v0 offset:9728
	v_add_f32_dpp v198, v198, v198 quad_perm:[1,0,3,2] row_mask:0xf bank_mask:0xf bound_ctrl:1
	v_add_f32_dpp v207, v207, v207 quad_perm:[1,0,3,2] row_mask:0xf bank_mask:0xf bound_ctrl:1
	v_pk_mul_f32 v[212:213], v[150:151], v[158:159] op_sel:[0,1] op_sel_hi:[1,1]
	v_add_f32_dpp v198, v198, v198 quad_perm:[2,3,0,1] row_mask:0xf bank_mask:0xf bound_ctrl:1
	v_add_f32_dpp v207, v207, v207 quad_perm:[2,3,0,1] row_mask:0xf bank_mask:0xf bound_ctrl:1
	v_pk_mul_f32 v[250:251], v[152:153], v[158:159] op_sel:[0,1] op_sel_hi:[1,1]
	ds_read_b128 v[150:153], v0 offset:9744
	v_add_f32_dpp v198, v198, v198 row_half_mirror row_mask:0xf bank_mask:0xf bound_ctrl:1
	v_add_f32_dpp v163, v207, v207 row_half_mirror row_mask:0xf bank_mask:0xf bound_ctrl:1
	ds_read2st64_b32 v[158:159], v161 offset0:6 offset1:7
	ds_write_b32 v162, v163 offset:512
	s_waitcnt lgkmcnt(9)
	v_pk_fma_f32 v[58:59], v[198:199], v[50:51], v[58:59] op_sel_hi:[0,1,1]
	v_pk_fma_f32 v[72:73], v[198:199], v[52:53], v[72:73] op_sel_hi:[0,1,1]
	s_waitcnt lgkmcnt(7)
	v_pk_fma_f32 v[66:67], v[66:67], v[42:43], v[58:59]
	v_pk_fma_f32 v[64:65], v[64:65], v[44:45], v[72:73]
	v_pk_fma_f32 v[212:213], v[198:199], v[54:55], v[212:213] op_sel_hi:[0,1,1]
	v_pk_fma_f32 v[250:251], v[198:199], v[56:57], v[250:251] op_sel_hi:[0,1,1]
	v_pk_fma_f32 v[62:63], v[62:63], v[46:47], v[212:213]
	v_pk_fma_f32 v[60:61], v[60:61], v[48:49], v[250:251]
	ds_read_b128 v[50:53], v0 offset:22016
	ds_read_b128 v[54:57], v0 offset:22032
	ds_read_b128 v[42:45], v0 offset:5632
	ds_read_b128 v[46:49], v0 offset:5648
	s_waitcnt lgkmcnt(9)
	v_pk_fma_f32 v[58:59], v[66:67], v[154:155], 0 op_sel_hi:[1,1,0]
	v_pk_fma_f32 v[72:73], v[64:65], v[156:157], 0 op_sel_hi:[1,1,0]
	v_pk_fma_f32 v[58:59], v[62:63], v[246:247], v[58:59]
	v_pk_fma_f32 v[72:73], v[60:61], v[248:249], v[72:73]
	ds_read_b128 v[154:157], v0 offset:1536
	ds_read_b128 v[246:249], v0 offset:1552
	v_add_f32_e32 v207, v58, v59
	v_add_f32_e32 v209, v72, v73
	ds_read_b128 v[200:203], v0 offset:18176
	ds_read_b128 v[230:233], v0 offset:18192
	s_waitcnt lgkmcnt(11)
	v_pk_mul_f32 v[34:35], v[66:67], v[34:35]
	v_pk_mul_f32 v[36:37], v[64:65], v[36:37]
	v_pk_fma_f32 v[34:35], v[62:63], v[38:39], v[34:35]
	v_pk_fma_f32 v[36:37], v[60:61], v[40:41], v[36:37]
	v_add_f32_e32 v198, v34, v35
	v_add_f32_e32 v199, v36, v37
	v_add_f32_e32 v207, v207, v209
	v_add_f32_e32 v198, v198, v199
	s_waitcnt lgkmcnt(8)
	v_pk_mul_f32 v[58:59], v[68:69], v[158:159] op_sel_hi:[1,0]
	v_pk_mul_f32 v[72:73], v[70:71], v[158:159] op_sel_hi:[1,0]
	ds_read_b128 v[68:71], v0 offset:9984
	v_add_f32_dpp v198, v198, v198 quad_perm:[1,0,3,2] row_mask:0xf bank_mask:0xf bound_ctrl:1
	v_add_f32_dpp v207, v207, v207 quad_perm:[1,0,3,2] row_mask:0xf bank_mask:0xf bound_ctrl:1
	v_pk_mul_f32 v[212:213], v[150:151], v[158:159] op_sel_hi:[1,0]
	v_add_f32_dpp v198, v198, v198 quad_perm:[2,3,0,1] row_mask:0xf bank_mask:0xf bound_ctrl:1
	v_add_f32_dpp v207, v207, v207 quad_perm:[2,3,0,1] row_mask:0xf bank_mask:0xf bound_ctrl:1
	v_pk_mul_f32 v[250:251], v[152:153], v[158:159] op_sel_hi:[1,0]
	ds_read_b128 v[150:153], v0 offset:10000
	v_add_f32_dpp v198, v198, v198 row_half_mirror row_mask:0xf bank_mask:0xf bound_ctrl:1
	v_add_f32_dpp v205, v207, v207 row_half_mirror row_mask:0xf bank_mask:0xf bound_ctrl:1
	ds_write_b32 v162, v205 offset:640
	s_waitcnt lgkmcnt(8)
	v_pk_fma_f32 v[58:59], v[198:199], v[50:51], v[58:59] op_sel_hi:[0,1,1]
	v_pk_fma_f32 v[72:73], v[198:199], v[52:53], v[72:73] op_sel_hi:[0,1,1]
	s_waitcnt lgkmcnt(6)
	v_pk_fma_f32 v[66:67], v[66:67], v[42:43], v[58:59]
	v_pk_fma_f32 v[64:65], v[64:65], v[44:45], v[72:73]
	v_pk_fma_f32 v[212:213], v[198:199], v[54:55], v[212:213] op_sel_hi:[0,1,1]
	v_pk_fma_f32 v[250:251], v[198:199], v[56:57], v[250:251] op_sel_hi:[0,1,1]
	v_pk_fma_f32 v[62:63], v[62:63], v[46:47], v[212:213]
	v_pk_fma_f32 v[60:61], v[60:61], v[48:49], v[250:251]
	ds_read_b128 v[50:53], v0 offset:22272
	ds_read_b128 v[54:57], v0 offset:22288
	ds_read_b128 v[42:45], v0 offset:5888
	ds_read_b128 v[46:49], v0 offset:5904
	s_waitcnt lgkmcnt(8)
; DI float oct_sum(float v) { v += dpp_f<0xB1>(v); v += dpp_f<0x4E>(v); v += dpp_f<0x141>(v); return v; }
; DI void scan_item(const Params& p, int b, int h, int half, char* smem, unsigned* pgen, unsigned kp) {
;     ...
;       for (int s4 = 0; s4 < 4; ++s4) {
;         const int s = sg + s4;
;         const f32x2* a2 = (const f32x2*)(Al + s * 64 + cg * 8);
;         const f32x2* w2 = (const f32x2*)(Wl + s * 64 + cg * 8);
;         const f32x2* b2 = (const f32x2*)(Bl + s * 64 + cg * 8);
;         const f32x2* k2 = (const f32x2*)(Kl + s * 64 + cg * 8);
;         const f32x2* r2 = (const f32x2*)(Rl + s * 64 + cg * 8);
;         f32x2 o[20];
; #pragma unroll
;         for (int i = 0; i < 4; ++i) { o[i] = a2[i]; o[4 + i] = w2[i]; o[8 + i] = b2[i]; o[12 + i] = k2[i]; o[16 + i] = r2[i]; }
;         const float vr = Vl[s * 64 + 32 * half + rp];
;         f32x2 p0 = St[0] * o[0], p1 = St[1] * o[1];
;         p0 = __builtin_elementwise_fma(St[2], o[2], p0); p1 = __builtin_elementwise_fma(St[3], o[3], p1);
;         const float sa = oct_sum((p0.x + p0.y) + (p1.x + p1.y));
;         const f32x2 sv = {sa, sa}, vv = {vr, vr};
;         f32x2 y0 = {0.f, 0.f}, y1 = {0.f, 0.f};
; #pragma unroll
;         for (int i = 0; i < 4; i += 2) {
;           St[i] = __builtin_elementwise_fma(St[i], o[4 + i], __builtin_elementwise_fma(sv, o[8 + i], vv * o[12 + i]));
;           St[i + 1] = __builtin_elementwise_fma(St[i + 1], o[5 + i], __builtin_elementwise_fma(sv, o[9 + i], vv * o[13 + i]));
;           y0 = __builtin_elementwise_fma(St[i], o[16 + i], y0);
;           y1 = __builtin_elementwise_fma(St[i + 1], o[17 + i], y1);
;         }
;         yy[s4] = oct_sum((y0.x + y0.y) + (y1.x + y1.y));
;       }
;       if (cg == 0) {
; #pragma unroll
;         for (int s4 = 0; s4 < 4; ++s4) Yl[(sg + s4) * 32 + rp] = yy[s4];
	v_pk_fma_f32 v[58:59], v[66:67], v[154:155], 0 op_sel_hi:[1,1,0]
	v_pk_fma_f32 v[72:73], v[64:65], v[156:157], 0 op_sel_hi:[1,1,0]
	v_pk_fma_f32 v[58:59], v[62:63], v[246:247], v[58:59]
	v_pk_fma_f32 v[72:73], v[60:61], v[248:249], v[72:73]
	ds_read_b128 v[154:157], v0 offset:1792
	ds_read_b128 v[246:249], v0 offset:1808
	v_add_f32_e32 v207, v58, v59
	v_add_f32_e32 v209, v72, v73
	ds_read_b128 v[34:37], v0 offset:18432
	ds_read_b128 v[38:41], v0 offset:18448
	s_waitcnt lgkmcnt(10)
	v_pk_mul_f32 v[200:201], v[66:67], v[200:201]
	v_pk_mul_f32 v[202:203], v[64:65], v[202:203]
	v_pk_fma_f32 v[200:201], v[62:63], v[230:231], v[200:201]
	v_pk_fma_f32 v[202:203], v[60:61], v[232:233], v[202:203]
	v_add_f32_e32 v198, v200, v201
	v_add_f32_e32 v199, v202, v203
	v_add_f32_e32 v207, v207, v209
	v_add_f32_e32 v198, v198, v199
	s_waitcnt lgkmcnt(8)
	v_pk_mul_f32 v[58:59], v[68:69], v[158:159] op_sel:[0,1] op_sel_hi:[1,1]
	v_pk_mul_f32 v[72:73], v[70:71], v[158:159] op_sel:[0,1] op_sel_hi:[1,1]
	ds_read_b128 v[68:71], v0 offset:10240
	v_add_f32_dpp v198, v198, v198 quad_perm:[1,0,3,2] row_mask:0xf bank_mask:0xf bound_ctrl:1
	v_add_f32_dpp v207, v207, v207 quad_perm:[1,0,3,2] row_mask:0xf bank_mask:0xf bound_ctrl:1
	v_pk_mul_f32 v[212:213], v[150:151], v[158:159] op_sel:[0,1] op_sel_hi:[1,1]
	v_add_f32_dpp v198, v198, v198 quad_perm:[2,3,0,1] row_mask:0xf bank_mask:0xf bound_ctrl:1
	v_add_f32_dpp v207, v207, v207 quad_perm:[2,3,0,1] row_mask:0xf bank_mask:0xf bound_ctrl:1
	v_pk_mul_f32 v[250:251], v[152:153], v[158:159] op_sel:[0,1] op_sel_hi:[1,1]
	ds_read_b128 v[150:153], v0 offset:10256
	v_add_f32_dpp v198, v198, v198 row_half_mirror row_mask:0xf bank_mask:0xf bound_ctrl:1
	v_add_f32_dpp v163, v207, v207 row_half_mirror row_mask:0xf bank_mask:0xf bound_ctrl:1
	ds_read2st64_b32 v[158:159], v161 offset0:8 offset1:9
	ds_write_b32 v162, v163 offset:768
	s_waitcnt lgkmcnt(9)
	v_pk_fma_f32 v[58:59], v[198:199], v[50:51], v[58:59] op_sel_hi:[0,1,1]
	v_pk_fma_f32 v[72:73], v[198:199], v[52:53], v[72:73] op_sel_hi:[0,1,1]
	s_waitcnt lgkmcnt(7)
	v_pk_fma_f32 v[66:67], v[66:67], v[42:43], v[58:59]
	v_pk_fma_f32 v[64:65], v[64:65], v[44:45], v[72:73]
	v_pk_fma_f32 v[212:213], v[198:199], v[54:55], v[212:213] op_sel_hi:[0,1,1]
	v_pk_fma_f32 v[250:251], v[198:199], v[56:57], v[250:251] op_sel_hi:[0,1,1]
	v_pk_fma_f32 v[62:63], v[62:63], v[46:47], v[212:213]
	v_pk_fma_f32 v[60:61], v[60:61], v[48:49], v[250:251]
	ds_read_b128 v[50:53], v0 offset:22528
	ds_read_b128 v[54:57], v0 offset:22544
	ds_read_b128 v[42:45], v0 offset:6144
	ds_read_b128 v[46:49], v0 offset:6160
	s_waitcnt lgkmcnt(9)
	v_pk_fma_f32 v[58:59], v[66:67], v[154:155], 0 op_sel_hi:[1,1,0]
	v_pk_fma_f32 v[72:73], v[64:65], v[156:157], 0 op_sel_hi:[1,1,0]
	v_pk_fma_f32 v[58:59], v[62:63], v[246:247], v[58:59]
	v_pk_fma_f32 v[72:73], v[60:61], v[248:249], v[72:73]
	ds_read_b128 v[154:157], v0 offset:2048
	ds_read_b128 v[246:249], v0 offset:2064
	v_add_f32_e32 v207, v58, v59
	v_add_f32_e32 v209, v72, v73
	ds_read_b128 v[200:203], v0 offset:18688
	ds_read_b128 v[230:233], v0 offset:18704
	s_waitcnt lgkmcnt(11)
	v_pk_mul_f32 v[34:35], v[66:67], v[34:35]
	v_pk_mul_f32 v[36:37], v[64:65], v[36:37]
	v_pk_fma_f32 v[34:35], v[62:63], v[38:39], v[34:35]
	v_pk_fma_f32 v[36:37], v[60:61], v[40:41], v[36:37]
	v_add_f32_e32 v198, v34, v35
	v_add_f32_e32 v199, v36, v37
	v_add_f32_e32 v207, v207, v209
	v_add_f32_e32 v198, v198, v199
	s_waitcnt lgkmcnt(8)
	v_pk_mul_f32 v[58:59], v[68:69], v[158:159] op_sel_hi:[1,0]
	v_pk_mul_f32 v[72:73], v[70:71], v[158:159] op_sel_hi:[1,0]
	ds_read_b128 v[68:71], v0 offset:10496
	v_add_f32_dpp v198, v198, v198 quad_perm:[1,0,3,2] row_mask:0xf bank_mask:0xf bound_ctrl:1
	v_add_f32_dpp v207, v207, v207 quad_perm:[1,0,3,2] row_mask:0xf bank_mask:0xf bound_ctrl:1
	v_pk_mul_f32 v[212:213], v[150:151], v[158:159] op_sel_hi:[1,0]
	v_add_f32_dpp v198, v198, v198 quad_perm:[2,3,0,1] row_mask:0xf bank_mask:0xf bound_ctrl:1
	v_add_f32_dpp v207, v207, v207 quad_perm:[2,3,0,1] row_mask:0xf bank_mask:0xf bound_ctrl:1
	v_pk_mul_f32 v[250:251], v[152:153], v[158:159] op_sel_hi:[1,0]
	ds_read_b128 v[150:153], v0 offset:10512
	v_add_f32_dpp v198, v198, v198 row_half_mirror row_mask:0xf bank_mask:0xf bound_ctrl:1
	v_add_f32_dpp v205, v207, v207 row_half_mirror row_mask:0xf bank_mask:0xf bound_ctrl:1
	ds_write_b32 v162, v205 offset:896
	s_waitcnt lgkmcnt(8)
	v_pk_fma_f32 v[58:59], v[198:199], v[50:51], v[58:59] op_sel_hi:[0,1,1]
	v_pk_fma_f32 v[72:73], v[198:199], v[52:53], v[72:73] op_sel_hi:[0,1,1]
	s_waitcnt lgkmcnt(6)
	v_pk_fma_f32 v[66:67], v[66:67], v[42:43], v[58:59]
	v_pk_fma_f32 v[64:65], v[64:65], v[44:45], v[72:73]
	v_pk_fma_f32 v[212:213], v[198:199], v[54:55], v[212:213] op_sel_hi:[0,1,1]
	v_pk_fma_f32 v[250:251], v[198:199], v[56:57], v[250:251] op_sel_hi:[0,1,1]
	v_pk_fma_f32 v[62:63], v[62:63], v[46:47], v[212:213]
	v_pk_fma_f32 v[60:61], v[60:61], v[48:49], v[250:251]
	ds_read_b128 v[50:53], v0 offset:22784
	ds_read_b128 v[54:57], v0 offset:22800
	ds_read_b128 v[42:45], v0 offset:6400
	ds_read_b128 v[46:49], v0 offset:6416
	s_waitcnt lgkmcnt(8)
	v_pk_fma_f32 v[58:59], v[66:67], v[154:155], 0 op_sel_hi:[1,1,0]
	v_pk_fma_f32 v[72:73], v[64:65], v[156:157], 0 op_sel_hi:[1,1,0]
	v_pk_fma_f32 v[58:59], v[62:63], v[246:247], v[58:59]
	v_pk_fma_f32 v[72:73], v[60:61], v[248:249], v[72:73]
	ds_read_b128 v[154:157], v0 offset:2304
	ds_read_b128 v[246:249], v0 offset:2320
	v_add_f32_e32 v207, v58, v59
	v_add_f32_e32 v209, v72, v73
	ds_read_b128 v[34:37], v0 offset:18944
	ds_read_b128 v[38:41], v0 offset:18960
	s_waitcnt lgkmcnt(10)
; DI float oct_sum(float v) { v += dpp_f<0xB1>(v); v += dpp_f<0x4E>(v); v += dpp_f<0x141>(v); return v; }
; DI void scan_item(const Params& p, int b, int h, int half, char* smem, unsigned* pgen, unsigned kp) {
;     ...
;       for (int s4 = 0; s4 < 4; ++s4) {
;         const int s = sg + s4;
;         const f32x2* a2 = (const f32x2*)(Al + s * 64 + cg * 8);
;         const f32x2* w2 = (const f32x2*)(Wl + s * 64 + cg * 8);
;         const f32x2* b2 = (const f32x2*)(Bl + s * 64 + cg * 8);
;         const f32x2* k2 = (const f32x2*)(Kl + s * 64 + cg * 8);
;         const f32x2* r2 = (const f32x2*)(Rl + s * 64 + cg * 8);
;         f32x2 o[20];
; #pragma unroll
;         for (int i = 0; i < 4; ++i) { o[i] = a2[i]; o[4 + i] = w2[i]; o[8 + i] = b2[i]; o[12 + i] = k2[i]; o[16 + i] = r2[i]; }
;         const float vr = Vl[s * 64 + 32 * half + rp];
;         f32x2 p0 = St[0] * o[0], p1 = St[1] * o[1];
;         p0 = __builtin_elementwise_fma(St[2], o[2], p0); p1 = __builtin_elementwise_fma(St[3], o[3], p1);
;         const float sa = oct_sum((p0.x + p0.y) + (p1.x + p1.y));
;         const f32x2 sv = {sa, sa}, vv = {vr, vr};
;         f32x2 y0 = {0.f, 0.f}, y1 = {0.f, 0.f};
; #pragma unroll
;         for (int i = 0; i < 4; i += 2) {
;           St[i] = __builtin_elementwise_fma(St[i], o[4 + i], __builtin_elementwise_fma(sv, o[8 + i], vv * o[12 + i]));
;           St[i + 1] = __builtin_elementwise_fma(St[i + 1], o[5 + i], __builtin_elementwise_fma(sv, o[9 + i], vv * o[13 + i]));
;           y0 = __builtin_elementwise_fma(St[i], o[16 + i], y0);
;           y1 = __builtin_elementwise_fma(St[i + 1], o[17 + i], y1);
;         }
;         yy[s4] = oct_sum((y0.x + y0.y) + (y1.x + y1.y));
;       }
;       if (cg == 0) {
; #pragma unroll
;         for (int s4 = 0; s4 < 4; ++s4) Yl[(sg + s4) * 32 + rp] = yy[s4];
	v_pk_mul_f32 v[200:201], v[66:67], v[200:201]
	v_pk_mul_f32 v[202:203], v[64:65], v[202:203]
	v_pk_fma_f32 v[200:201], v[62:63], v[230:231], v[200:201]
	v_pk_fma_f32 v[202:203], v[60:61], v[232:233], v[202:203]
	v_add_f32_e32 v198, v200, v201
	v_add_f32_e32 v199, v202, v203
	v_add_f32_e32 v207, v207, v209
	v_add_f32_e32 v198, v198, v199
	s_waitcnt lgkmcnt(8)
	v_pk_mul_f32 v[58:59], v[68:69], v[158:159] op_sel:[0,1] op_sel_hi:[1,1]
	v_pk_mul_f32 v[72:73], v[70:71], v[158:159] op_sel:[0,1] op_sel_hi:[1,1]
	ds_read_b128 v[68:71], v0 offset:10752
	v_add_f32_dpp v198, v198, v198 quad_perm:[1,0,3,2] row_mask:0xf bank_mask:0xf bound_ctrl:1
	v_add_f32_dpp v207, v207, v207 quad_perm:[1,0,3,2] row_mask:0xf bank_mask:0xf bound_ctrl:1
	v_pk_mul_f32 v[212:213], v[150:151], v[158:159] op_sel:[0,1] op_sel_hi:[1,1]
	v_add_f32_dpp v198, v198, v198 quad_perm:[2,3,0,1] row_mask:0xf bank_mask:0xf bound_ctrl:1
	v_add_f32_dpp v207, v207, v207 quad_perm:[2,3,0,1] row_mask:0xf bank_mask:0xf bound_ctrl:1
	v_pk_mul_f32 v[250:251], v[152:153], v[158:159] op_sel:[0,1] op_sel_hi:[1,1]
	ds_read_b128 v[150:153], v0 offset:10768
	v_add_f32_dpp v198, v198, v198 row_half_mirror row_mask:0xf bank_mask:0xf bound_ctrl:1
	v_add_f32_dpp v163, v207, v207 row_half_mirror row_mask:0xf bank_mask:0xf bound_ctrl:1
	ds_read2st64_b32 v[158:159], v161 offset0:10 offset1:11
	ds_write_b32 v162, v163 offset:1024
	s_waitcnt lgkmcnt(9)
	v_pk_fma_f32 v[58:59], v[198:199], v[50:51], v[58:59] op_sel_hi:[0,1,1]
	v_pk_fma_f32 v[72:73], v[198:199], v[52:53], v[72:73] op_sel_hi:[0,1,1]
	s_waitcnt lgkmcnt(7)
	v_pk_fma_f32 v[66:67], v[66:67], v[42:43], v[58:59]
	v_pk_fma_f32 v[64:65], v[64:65], v[44:45], v[72:73]
	v_pk_fma_f32 v[212:213], v[198:199], v[54:55], v[212:213] op_sel_hi:[0,1,1]
	v_pk_fma_f32 v[250:251], v[198:199], v[56:57], v[250:251] op_sel_hi:[0,1,1]
	v_pk_fma_f32 v[62:63], v[62:63], v[46:47], v[212:213]
	v_pk_fma_f32 v[60:61], v[60:61], v[48:49], v[250:251]
	ds_read_b128 v[50:53], v0 offset:23040
	ds_read_b128 v[54:57], v0 offset:23056
	ds_read_b128 v[42:45], v0 offset:6656
	ds_read_b128 v[46:49], v0 offset:6672
	s_waitcnt lgkmcnt(9)
	v_pk_fma_f32 v[58:59], v[66:67], v[154:155], 0 op_sel_hi:[1,1,0]
	v_pk_fma_f32 v[72:73], v[64:65], v[156:157], 0 op_sel_hi:[1,1,0]
	v_pk_fma_f32 v[58:59], v[62:63], v[246:247], v[58:59]
	v_pk_fma_f32 v[72:73], v[60:61], v[248:249], v[72:73]
	ds_read_b128 v[154:157], v0 offset:2560
	ds_read_b128 v[246:249], v0 offset:2576
	v_add_f32_e32 v207, v58, v59
	v_add_f32_e32 v209, v72, v73
	ds_read_b128 v[200:203], v0 offset:19200
	ds_read_b128 v[230:233], v0 offset:19216
	s_waitcnt lgkmcnt(11)
	v_pk_mul_f32 v[34:35], v[66:67], v[34:35]
	v_pk_mul_f32 v[36:37], v[64:65], v[36:37]
	v_pk_fma_f32 v[34:35], v[62:63], v[38:39], v[34:35]
	v_pk_fma_f32 v[36:37], v[60:61], v[40:41], v[36:37]
	v_add_f32_e32 v198, v34, v35
	v_add_f32_e32 v199, v36, v37
	v_add_f32_e32 v207, v207, v209
	v_add_f32_e32 v198, v198, v199
	s_waitcnt lgkmcnt(8)
	v_pk_mul_f32 v[58:59], v[68:69], v[158:159] op_sel_hi:[1,0]
	v_pk_mul_f32 v[72:73], v[70:71], v[158:159] op_sel_hi:[1,0]
	ds_read_b128 v[68:71], v0 offset:11008
	v_add_f32_dpp v198, v198, v198 quad_perm:[1,0,3,2] row_mask:0xf bank_mask:0xf bound_ctrl:1
	v_add_f32_dpp v207, v207, v207 quad_perm:[1,0,3,2] row_mask:0xf bank_mask:0xf bound_ctrl:1
	v_pk_mul_f32 v[212:213], v[150:151], v[158:159] op_sel_hi:[1,0]
	v_add_f32_dpp v198, v198, v198 quad_perm:[2,3,0,1] row_mask:0xf bank_mask:0xf bound_ctrl:1
	v_add_f32_dpp v207, v207, v207 quad_perm:[2,3,0,1] row_mask:0xf bank_mask:0xf bound_ctrl:1
	v_pk_mul_f32 v[250:251], v[152:153], v[158:159] op_sel_hi:[1,0]
	ds_read_b128 v[150:153], v0 offset:11024
	v_add_f32_dpp v198, v198, v198 row_half_mirror row_mask:0xf bank_mask:0xf bound_ctrl:1
	v_add_f32_dpp v205, v207, v207 row_half_mirror row_mask:0xf bank_mask:0xf bound_ctrl:1
	ds_write_b32 v162, v205 offset:1152
	s_waitcnt lgkmcnt(8)
	v_pk_fma_f32 v[58:59], v[198:199], v[50:51], v[58:59] op_sel_hi:[0,1,1]
	v_pk_fma_f32 v[72:73], v[198:199], v[52:53], v[72:73] op_sel_hi:[0,1,1]
	s_waitcnt lgkmcnt(6)
	v_pk_fma_f32 v[66:67], v[66:67], v[42:43], v[58:59]
	v_pk_fma_f32 v[64:65], v[64:65], v[44:45], v[72:73]
	v_pk_fma_f32 v[212:213], v[198:199], v[54:55], v[212:213] op_sel_hi:[0,1,1]
	v_pk_fma_f32 v[250:251], v[198:199], v[56:57], v[250:251] op_sel_hi:[0,1,1]
	v_pk_fma_f32 v[62:63], v[62:63], v[46:47], v[212:213]
	v_pk_fma_f32 v[60:61], v[60:61], v[48:49], v[250:251]
	ds_read_b128 v[50:53], v0 offset:23296
	ds_read_b128 v[54:57], v0 offset:23312
	ds_read_b128 v[42:45], v0 offset:6912
	ds_read_b128 v[46:49], v0 offset:6928
	s_waitcnt lgkmcnt(8)
	v_pk_fma_f32 v[58:59], v[66:67], v[154:155], 0 op_sel_hi:[1,1,0]
	v_pk_fma_f32 v[72:73], v[64:65], v[156:157], 0 op_sel_hi:[1,1,0]
	v_pk_fma_f32 v[58:59], v[62:63], v[246:247], v[58:59]
	v_pk_fma_f32 v[72:73], v[60:61], v[248:249], v[72:73]
	ds_read_b128 v[154:157], v0 offset:2816
	ds_read_b128 v[246:249], v0 offset:2832
	v_add_f32_e32 v207, v58, v59
	v_add_f32_e32 v209, v72, v73
	ds_read_b128 v[34:37], v0 offset:19456
	ds_read_b128 v[38:41], v0 offset:19472
	s_waitcnt lgkmcnt(10)
	v_pk_mul_f32 v[200:201], v[66:67], v[200:201]
	v_pk_mul_f32 v[202:203], v[64:65], v[202:203]
	v_pk_fma_f32 v[200:201], v[62:63], v[230:231], v[200:201]
	v_pk_fma_f32 v[202:203], v[60:61], v[232:233], v[202:203]
	v_add_f32_e32 v198, v200, v201
	v_add_f32_e32 v199, v202, v203
	v_add_f32_e32 v207, v207, v209
	v_add_f32_e32 v198, v198, v199
	s_waitcnt lgkmcnt(8)
; DI float oct_sum(float v) { v += dpp_f<0xB1>(v); v += dpp_f<0x4E>(v); v += dpp_f<0x141>(v); return v; }
; DI void scan_item(const Params& p, int b, int h, int half, char* smem, unsigned* pgen, unsigned kp) {
;     ...
;       for (int s4 = 0; s4 < 4; ++s4) {
;         const int s = sg + s4;
;         const f32x2* a2 = (const f32x2*)(Al + s * 64 + cg * 8);
;         const f32x2* w2 = (const f32x2*)(Wl + s * 64 + cg * 8);
;         const f32x2* b2 = (const f32x2*)(Bl + s * 64 + cg * 8);
;         const f32x2* k2 = (const f32x2*)(Kl + s * 64 + cg * 8);
;         const f32x2* r2 = (const f32x2*)(Rl + s * 64 + cg * 8);
;         f32x2 o[20];
; #pragma unroll
;         for (int i = 0; i < 4; ++i) { o[i] = a2[i]; o[4 + i] = w2[i]; o[8 + i] = b2[i]; o[12 + i] = k2[i]; o[16 + i] = r2[i]; }
;         const float vr = Vl[s * 64 + 32 * half + rp];
;         f32x2 p0 = St[0] * o[0], p1 = St[1] * o[1];
;         p0 = __builtin_elementwise_fma(St[2], o[2], p0); p1 = __builtin_elementwise_fma(St[3], o[3], p1);
;         const float sa = oct_sum((p0.x + p0.y) + (p1.x + p1.y));
;         const f32x2 sv = {sa, sa}, vv = {vr, vr};
;         f32x2 y0 = {0.f, 0.f}, y1 = {0.f, 0.f};
; #pragma unroll
;         for (int i = 0; i < 4; i += 2) {
;           St[i] = __builtin_elementwise_fma(St[i], o[4 + i], __builtin_elementwise_fma(sv, o[8 + i], vv * o[12 + i]));
;           St[i + 1] = __builtin_elementwise_fma(St[i + 1], o[5 + i], __builtin_elementwise_fma(sv, o[9 + i], vv * o[13 + i]));
;           y0 = __builtin_elementwise_fma(St[i], o[16 + i], y0);
;           y1 = __builtin_elementwise_fma(St[i + 1], o[17 + i], y1);
;         }
;         yy[s4] = oct_sum((y0.x + y0.y) + (y1.x + y1.y));
;       }
;       if (cg == 0) {
; #pragma unroll
;         for (int s4 = 0; s4 < 4; ++s4) Yl[(sg + s4) * 32 + rp] = yy[s4];
	v_pk_mul_f32 v[58:59], v[68:69], v[158:159] op_sel:[0,1] op_sel_hi:[1,1]
	v_pk_mul_f32 v[72:73], v[70:71], v[158:159] op_sel:[0,1] op_sel_hi:[1,1]
	ds_read_b128 v[68:71], v0 offset:11264
	v_add_f32_dpp v198, v198, v198 quad_perm:[1,0,3,2] row_mask:0xf bank_mask:0xf bound_ctrl:1
	v_add_f32_dpp v207, v207, v207 quad_perm:[1,0,3,2] row_mask:0xf bank_mask:0xf bound_ctrl:1
	v_pk_mul_f32 v[212:213], v[150:151], v[158:159] op_sel:[0,1] op_sel_hi:[1,1]
	v_add_f32_dpp v198, v198, v198 quad_perm:[2,3,0,1] row_mask:0xf bank_mask:0xf bound_ctrl:1
	v_add_f32_dpp v207, v207, v207 quad_perm:[2,3,0,1] row_mask:0xf bank_mask:0xf bound_ctrl:1
	v_pk_mul_f32 v[250:251], v[152:153], v[158:159] op_sel:[0,1] op_sel_hi:[1,1]
	ds_read_b128 v[150:153], v0 offset:11280
	v_add_f32_dpp v198, v198, v198 row_half_mirror row_mask:0xf bank_mask:0xf bound_ctrl:1
	v_add_f32_dpp v163, v207, v207 row_half_mirror row_mask:0xf bank_mask:0xf bound_ctrl:1
	ds_read2st64_b32 v[158:159], v161 offset0:12 offset1:13
	ds_write_b32 v162, v163 offset:1280
	s_waitcnt lgkmcnt(9)
	v_pk_fma_f32 v[58:59], v[198:199], v[50:51], v[58:59] op_sel_hi:[0,1,1]
	v_pk_fma_f32 v[72:73], v[198:199], v[52:53], v[72:73] op_sel_hi:[0,1,1]
	s_waitcnt lgkmcnt(7)
	v_pk_fma_f32 v[66:67], v[66:67], v[42:43], v[58:59]
	v_pk_fma_f32 v[64:65], v[64:65], v[44:45], v[72:73]
	v_pk_fma_f32 v[212:213], v[198:199], v[54:55], v[212:213] op_sel_hi:[0,1,1]
	v_pk_fma_f32 v[250:251], v[198:199], v[56:57], v[250:251] op_sel_hi:[0,1,1]
	v_pk_fma_f32 v[62:63], v[62:63], v[46:47], v[212:213]
	v_pk_fma_f32 v[60:61], v[60:61], v[48:49], v[250:251]
	ds_read_b128 v[50:53], v0 offset:23552
	ds_read_b128 v[54:57], v0 offset:23568
	ds_read_b128 v[42:45], v0 offset:7168
	ds_read_b128 v[46:49], v0 offset:7184
	s_waitcnt lgkmcnt(9)
	v_pk_fma_f32 v[58:59], v[66:67], v[154:155], 0 op_sel_hi:[1,1,0]
	v_pk_fma_f32 v[72:73], v[64:65], v[156:157], 0 op_sel_hi:[1,1,0]
	v_pk_fma_f32 v[58:59], v[62:63], v[246:247], v[58:59]
	v_pk_fma_f32 v[72:73], v[60:61], v[248:249], v[72:73]
	ds_read_b128 v[154:157], v0 offset:3072
	ds_read_b128 v[246:249], v0 offset:3088
	v_add_f32_e32 v207, v58, v59
	v_add_f32_e32 v209, v72, v73
	ds_read_b128 v[200:203], v0 offset:19712
	ds_read_b128 v[230:233], v0 offset:19728
	s_waitcnt lgkmcnt(11)
	v_pk_mul_f32 v[34:35], v[66:67], v[34:35]
	v_pk_mul_f32 v[36:37], v[64:65], v[36:37]
	v_pk_fma_f32 v[34:35], v[62:63], v[38:39], v[34:35]
	v_pk_fma_f32 v[36:37], v[60:61], v[40:41], v[36:37]
	v_add_f32_e32 v198, v34, v35
	v_add_f32_e32 v199, v36, v37
	v_add_f32_e32 v207, v207, v209
	v_add_f32_e32 v198, v198, v199
	s_waitcnt lgkmcnt(8)
	v_pk_mul_f32 v[58:59], v[68:69], v[158:159] op_sel_hi:[1,0]
	v_pk_mul_f32 v[72:73], v[70:71], v[158:159] op_sel_hi:[1,0]
	ds_read_b128 v[68:71], v0 offset:11520
	v_add_f32_dpp v198, v198, v198 quad_perm:[1,0,3,2] row_mask:0xf bank_mask:0xf bound_ctrl:1
	v_add_f32_dpp v207, v207, v207 quad_perm:[1,0,3,2] row_mask:0xf bank_mask:0xf bound_ctrl:1
	v_pk_mul_f32 v[212:213], v[150:151], v[158:159] op_sel_hi:[1,0]
	v_add_f32_dpp v198, v198, v198 quad_perm:[2,3,0,1] row_mask:0xf bank_mask:0xf bound_ctrl:1
	v_add_f32_dpp v207, v207, v207 quad_perm:[2,3,0,1] row_mask:0xf bank_mask:0xf bound_ctrl:1
	v_pk_mul_f32 v[250:251], v[152:153], v[158:159] op_sel_hi:[1,0]
	ds_read_b128 v[150:153], v0 offset:11536
	v_add_f32_dpp v198, v198, v198 row_half_mirror row_mask:0xf bank_mask:0xf bound_ctrl:1
	v_add_f32_dpp v205, v207, v207 row_half_mirror row_mask:0xf bank_mask:0xf bound_ctrl:1
	ds_write_b32 v162, v205 offset:1408
	s_waitcnt lgkmcnt(8)
	v_pk_fma_f32 v[58:59], v[198:199], v[50:51], v[58:59] op_sel_hi:[0,1,1]
	v_pk_fma_f32 v[72:73], v[198:199], v[52:53], v[72:73] op_sel_hi:[0,1,1]
	s_waitcnt lgkmcnt(6)
	v_pk_fma_f32 v[66:67], v[66:67], v[42:43], v[58:59]
	v_pk_fma_f32 v[64:65], v[64:65], v[44:45], v[72:73]
	v_pk_fma_f32 v[212:213], v[198:199], v[54:55], v[212:213] op_sel_hi:[0,1,1]
	v_pk_fma_f32 v[250:251], v[198:199], v[56:57], v[250:251] op_sel_hi:[0,1,1]
	v_pk_fma_f32 v[62:63], v[62:63], v[46:47], v[212:213]
	v_pk_fma_f32 v[60:61], v[60:61], v[48:49], v[250:251]
	ds_read_b128 v[50:53], v0 offset:23808
	ds_read_b128 v[54:57], v0 offset:23824
	ds_read_b128 v[42:45], v0 offset:7424
	ds_read_b128 v[46:49], v0 offset:7440
	s_waitcnt lgkmcnt(8)
	v_pk_fma_f32 v[58:59], v[66:67], v[154:155], 0 op_sel_hi:[1,1,0]
	v_pk_fma_f32 v[72:73], v[64:65], v[156:157], 0 op_sel_hi:[1,1,0]
	v_pk_fma_f32 v[58:59], v[62:63], v[246:247], v[58:59]
	v_pk_fma_f32 v[72:73], v[60:61], v[248:249], v[72:73]
	ds_read_b128 v[154:157], v0 offset:3328
	ds_read_b128 v[246:249], v0 offset:3344
	v_add_f32_e32 v207, v58, v59
	v_add_f32_e32 v209, v72, v73
	ds_read_b128 v[34:37], v0 offset:19968
	ds_read_b128 v[38:41], v0 offset:19984
	s_waitcnt lgkmcnt(10)
	v_pk_mul_f32 v[200:201], v[66:67], v[200:201]
	v_pk_mul_f32 v[202:203], v[64:65], v[202:203]
	v_pk_fma_f32 v[200:201], v[62:63], v[230:231], v[200:201]
	v_pk_fma_f32 v[202:203], v[60:61], v[232:233], v[202:203]
	v_add_f32_e32 v198, v200, v201
	v_add_f32_e32 v199, v202, v203
	v_add_f32_e32 v207, v207, v209
	v_add_f32_e32 v198, v198, v199
	s_waitcnt lgkmcnt(8)
	v_pk_mul_f32 v[58:59], v[68:69], v[158:159] op_sel:[0,1] op_sel_hi:[1,1]
	v_pk_mul_f32 v[72:73], v[70:71], v[158:159] op_sel:[0,1] op_sel_hi:[1,1]
	ds_read_b128 v[68:71], v0 offset:11776
	v_add_f32_dpp v198, v198, v198 quad_perm:[1,0,3,2] row_mask:0xf bank_mask:0xf bound_ctrl:1
	v_add_f32_dpp v207, v207, v207 quad_perm:[1,0,3,2] row_mask:0xf bank_mask:0xf bound_ctrl:1
	v_pk_mul_f32 v[212:213], v[150:151], v[158:159] op_sel:[0,1] op_sel_hi:[1,1]
	v_add_f32_dpp v198, v198, v198 quad_perm:[2,3,0,1] row_mask:0xf bank_mask:0xf bound_ctrl:1
	v_add_f32_dpp v207, v207, v207 quad_perm:[2,3,0,1] row_mask:0xf bank_mask:0xf bound_ctrl:1
	v_pk_mul_f32 v[250:251], v[152:153], v[158:159] op_sel:[0,1] op_sel_hi:[1,1]
	ds_read_b128 v[150:153], v0 offset:11792
	v_add_f32_dpp v198, v198, v198 row_half_mirror row_mask:0xf bank_mask:0xf bound_ctrl:1
	v_add_f32_dpp v163, v207, v207 row_half_mirror row_mask:0xf bank_mask:0xf bound_ctrl:1
	ds_read2st64_b32 v[158:159], v161 offset0:14 offset1:15
	ds_write_b32 v162, v163 offset:1536
	s_waitcnt lgkmcnt(9)
; DI float oct_sum(float v) { v += dpp_f<0xB1>(v); v += dpp_f<0x4E>(v); v += dpp_f<0x141>(v); return v; }
; DI void scan_item(const Params& p, int b, int h, int half, char* smem, unsigned* pgen, unsigned kp) {
;     ...
;       for (int s4 = 0; s4 < 4; ++s4) {
;         const int s = sg + s4;
;         const f32x2* a2 = (const f32x2*)(Al + s * 64 + cg * 8);
;         const f32x2* w2 = (const f32x2*)(Wl + s * 64 + cg * 8);
;         const f32x2* b2 = (const f32x2*)(Bl + s * 64 + cg * 8);
;         const f32x2* k2 = (const f32x2*)(Kl + s * 64 + cg * 8);
;         const f32x2* r2 = (const f32x2*)(Rl + s * 64 + cg * 8);
;         f32x2 o[20];
; #pragma unroll
;         for (int i = 0; i < 4; ++i) { o[i] = a2[i]; o[4 + i] = w2[i]; o[8 + i] = b2[i]; o[12 + i] = k2[i]; o[16 + i] = r2[i]; }
;         const float vr = Vl[s * 64 + 32 * half + rp];
;         f32x2 p0 = St[0] * o[0], p1 = St[1] * o[1];
;         p0 = __builtin_elementwise_fma(St[2], o[2], p0); p1 = __builtin_elementwise_fma(St[3], o[3], p1);
;         const float sa = oct_sum((p0.x + p0.y) + (p1.x + p1.y));
;         const f32x2 sv = {sa, sa}, vv = {vr, vr};
;         f32x2 y0 = {0.f, 0.f}, y1 = {0.f, 0.f};
; #pragma unroll
;         for (int i = 0; i < 4; i += 2) {
;           St[i] = __builtin_elementwise_fma(St[i], o[4 + i], __builtin_elementwise_fma(sv, o[8 + i], vv * o[12 + i]));
;           St[i + 1] = __builtin_elementwise_fma(St[i + 1], o[5 + i], __builtin_elementwise_fma(sv, o[9 + i], vv * o[13 + i]));
;           y0 = __builtin_elementwise_fma(St[i], o[16 + i], y0);
;           y1 = __builtin_elementwise_fma(St[i + 1], o[17 + i], y1);
;         }
;         yy[s4] = oct_sum((y0.x + y0.y) + (y1.x + y1.y));
;       }
;       if (cg == 0) {
; #pragma unroll
;         for (int s4 = 0; s4 < 4; ++s4) Yl[(sg + s4) * 32 + rp] = yy[s4];
	v_pk_fma_f32 v[58:59], v[198:199], v[50:51], v[58:59] op_sel_hi:[0,1,1]
	v_pk_fma_f32 v[72:73], v[198:199], v[52:53], v[72:73] op_sel_hi:[0,1,1]
	s_waitcnt lgkmcnt(7)
	v_pk_fma_f32 v[66:67], v[66:67], v[42:43], v[58:59]
	v_pk_fma_f32 v[64:65], v[64:65], v[44:45], v[72:73]
	v_pk_fma_f32 v[212:213], v[198:199], v[54:55], v[212:213] op_sel_hi:[0,1,1]
	v_pk_fma_f32 v[250:251], v[198:199], v[56:57], v[250:251] op_sel_hi:[0,1,1]
	v_pk_fma_f32 v[62:63], v[62:63], v[46:47], v[212:213]
	v_pk_fma_f32 v[60:61], v[60:61], v[48:49], v[250:251]
	ds_read_b128 v[50:53], v0 offset:24064
	ds_read_b128 v[54:57], v0 offset:24080
	ds_read_b128 v[42:45], v0 offset:7680
	ds_read_b128 v[46:49], v0 offset:7696
	s_waitcnt lgkmcnt(9)
	v_pk_fma_f32 v[58:59], v[66:67], v[154:155], 0 op_sel_hi:[1,1,0]
	v_pk_fma_f32 v[72:73], v[64:65], v[156:157], 0 op_sel_hi:[1,1,0]
	v_pk_fma_f32 v[58:59], v[62:63], v[246:247], v[58:59]
	v_pk_fma_f32 v[72:73], v[60:61], v[248:249], v[72:73]
	ds_read_b128 v[154:157], v0 offset:3584
	ds_read_b128 v[246:249], v0 offset:3600
	v_add_f32_e32 v207, v58, v59
	v_add_f32_e32 v209, v72, v73
	ds_read_b128 v[200:203], v0 offset:20224
	ds_read_b128 v[230:233], v0 offset:20240
	s_waitcnt lgkmcnt(11)
	v_pk_mul_f32 v[34:35], v[66:67], v[34:35]
	v_pk_mul_f32 v[36:37], v[64:65], v[36:37]
	v_pk_fma_f32 v[34:35], v[62:63], v[38:39], v[34:35]
	v_pk_fma_f32 v[36:37], v[60:61], v[40:41], v[36:37]
	v_add_f32_e32 v198, v34, v35
	v_add_f32_e32 v199, v36, v37
	v_add_f32_e32 v207, v207, v209
	v_add_f32_e32 v198, v198, v199
	s_waitcnt lgkmcnt(8)
	v_pk_mul_f32 v[58:59], v[68:69], v[158:159] op_sel_hi:[1,0]
	v_pk_mul_f32 v[72:73], v[70:71], v[158:159] op_sel_hi:[1,0]
	ds_read_b128 v[68:71], v0 offset:12032
	v_add_f32_dpp v198, v198, v198 quad_perm:[1,0,3,2] row_mask:0xf bank_mask:0xf bound_ctrl:1
	v_add_f32_dpp v207, v207, v207 quad_perm:[1,0,3,2] row_mask:0xf bank_mask:0xf bound_ctrl:1
	v_pk_mul_f32 v[212:213], v[150:151], v[158:159] op_sel_hi:[1,0]
	v_add_f32_dpp v198, v198, v198 quad_perm:[2,3,0,1] row_mask:0xf bank_mask:0xf bound_ctrl:1
	v_add_f32_dpp v207, v207, v207 quad_perm:[2,3,0,1] row_mask:0xf bank_mask:0xf bound_ctrl:1
	v_pk_mul_f32 v[250:251], v[152:153], v[158:159] op_sel_hi:[1,0]
	ds_read_b128 v[150:153], v0 offset:12048
	v_add_f32_dpp v198, v198, v198 row_half_mirror row_mask:0xf bank_mask:0xf bound_ctrl:1
	v_add_f32_dpp v205, v207, v207 row_half_mirror row_mask:0xf bank_mask:0xf bound_ctrl:1
	ds_write_b32 v162, v205 offset:1664
	s_waitcnt lgkmcnt(8)
	v_pk_fma_f32 v[58:59], v[198:199], v[50:51], v[58:59] op_sel_hi:[0,1,1]
	v_pk_fma_f32 v[72:73], v[198:199], v[52:53], v[72:73] op_sel_hi:[0,1,1]
	s_waitcnt lgkmcnt(6)
	v_pk_fma_f32 v[66:67], v[66:67], v[42:43], v[58:59]
	v_pk_fma_f32 v[64:65], v[64:65], v[44:45], v[72:73]
	v_pk_fma_f32 v[212:213], v[198:199], v[54:55], v[212:213] op_sel_hi:[0,1,1]
	v_pk_fma_f32 v[250:251], v[198:199], v[56:57], v[250:251] op_sel_hi:[0,1,1]
	v_pk_fma_f32 v[62:63], v[62:63], v[46:47], v[212:213]
	v_pk_fma_f32 v[60:61], v[60:61], v[48:49], v[250:251]
	ds_read_b128 v[50:53], v0 offset:24320
	ds_read_b128 v[54:57], v0 offset:24336
	ds_read_b128 v[42:45], v0 offset:7936
	ds_read_b128 v[46:49], v0 offset:7952
	s_waitcnt lgkmcnt(8)
	v_pk_fma_f32 v[58:59], v[66:67], v[154:155], 0 op_sel_hi:[1,1,0]
	v_pk_fma_f32 v[72:73], v[64:65], v[156:157], 0 op_sel_hi:[1,1,0]
	v_pk_fma_f32 v[58:59], v[62:63], v[246:247], v[58:59]
	v_pk_fma_f32 v[72:73], v[60:61], v[248:249], v[72:73]
	ds_read_b128 v[154:157], v0 offset:3840
	ds_read_b128 v[246:249], v0 offset:3856
	v_add_f32_e32 v207, v58, v59
	v_add_f32_e32 v209, v72, v73
	s_waitcnt lgkmcnt(8)
	v_pk_mul_f32 v[200:201], v[66:67], v[200:201]
	v_pk_mul_f32 v[202:203], v[64:65], v[202:203]
	v_pk_fma_f32 v[200:201], v[62:63], v[230:231], v[200:201]
	v_pk_fma_f32 v[202:203], v[60:61], v[232:233], v[202:203]
	v_add_f32_e32 v198, v200, v201
	v_add_f32_e32 v199, v202, v203
	v_add_f32_e32 v207, v207, v209
	v_add_f32_e32 v198, v198, v199
	s_waitcnt lgkmcnt(6)
	v_pk_mul_f32 v[58:59], v[68:69], v[158:159] op_sel:[0,1] op_sel_hi:[1,1]
	v_pk_mul_f32 v[72:73], v[70:71], v[158:159] op_sel:[0,1] op_sel_hi:[1,1]
	v_add_f32_dpp v198, v198, v198 quad_perm:[1,0,3,2] row_mask:0xf bank_mask:0xf bound_ctrl:1
	v_add_f32_dpp v207, v207, v207 quad_perm:[1,0,3,2] row_mask:0xf bank_mask:0xf bound_ctrl:1
	v_pk_mul_f32 v[212:213], v[150:151], v[158:159] op_sel:[0,1] op_sel_hi:[1,1]
	v_add_f32_dpp v198, v198, v198 quad_perm:[2,3,0,1] row_mask:0xf bank_mask:0xf bound_ctrl:1
	v_add_f32_dpp v207, v207, v207 quad_perm:[2,3,0,1] row_mask:0xf bank_mask:0xf bound_ctrl:1
	v_pk_mul_f32 v[250:251], v[152:153], v[158:159] op_sel:[0,1] op_sel_hi:[1,1]
	v_add_f32_dpp v198, v198, v198 row_half_mirror row_mask:0xf bank_mask:0xf bound_ctrl:1
	v_add_f32_dpp v163, v207, v207 row_half_mirror row_mask:0xf bank_mask:0xf bound_ctrl:1
	ds_write_b32 v162, v163 offset:1792
	s_waitcnt lgkmcnt(4)
	v_pk_fma_f32 v[58:59], v[198:199], v[50:51], v[58:59] op_sel_hi:[0,1,1]
	v_pk_fma_f32 v[72:73], v[198:199], v[52:53], v[72:73] op_sel_hi:[0,1,1]
	s_waitcnt lgkmcnt(2)
	v_pk_fma_f32 v[66:67], v[66:67], v[42:43], v[58:59]
	v_pk_fma_f32 v[64:65], v[64:65], v[44:45], v[72:73]
	v_pk_fma_f32 v[212:213], v[198:199], v[54:55], v[212:213] op_sel_hi:[0,1,1]
	v_pk_fma_f32 v[250:251], v[198:199], v[56:57], v[250:251] op_sel_hi:[0,1,1]
	v_pk_fma_f32 v[62:63], v[62:63], v[46:47], v[212:213]
	v_pk_fma_f32 v[60:61], v[60:61], v[48:49], v[250:251]
	s_waitcnt lgkmcnt(0)
	v_pk_fma_f32 v[58:59], v[66:67], v[154:155], 0 op_sel_hi:[1,1,0]
	v_pk_fma_f32 v[72:73], v[64:65], v[156:157], 0 op_sel_hi:[1,1,0]
	v_pk_fma_f32 v[58:59], v[62:63], v[246:247], v[58:59]
	v_pk_fma_f32 v[72:73], v[60:61], v[248:249], v[72:73]
	v_add_f32_e32 v207, v58, v59
	v_add_f32_e32 v209, v72, v73
	v_add_f32_e32 v207, v207, v209
	s_nop 1
	v_add_f32_dpp v207, v207, v207 quad_perm:[1,0,3,2] row_mask:0xf bank_mask:0xf bound_ctrl:1
	s_nop 1
	v_add_f32_dpp v207, v207, v207 quad_perm:[2,3,0,1] row_mask:0xf bank_mask:0xf bound_ctrl:1
	s_nop 1
	v_add_f32_dpp v205, v207, v207 row_half_mirror row_mask:0xf bank_mask:0xf bound_ctrl:1
	ds_write_b32 v162, v205 offset:1920

; DI float oct_sum(float v) { v += dpp_f<0xB1>(v); v += dpp_f<0x4E>(v); v += dpp_f<0x141>(v); return v; }
; DI void scan_item(const Params& p, int b, int h, int half, char* smem, unsigned* pgen, unsigned kp) {
;     ...
;     for (int sg = 0; sg < SC; sg += 4) {
;       float yy[4];
; #pragma unroll
;       for (int s4 = 0; s4 < 4; ++s4) {
;         const int s = sg + s4;
;         const f32x2* a2 = (const f32x2*)(Al + s * 64 + cg * 8);
;         const f32x2* w2 = (const f32x2*)(Wl + s * 64 + cg * 8);
;         const f32x2* b2 = (const f32x2*)(Bl + s * 64 + cg * 8);
;         const f32x2* k2 = (const f32x2*)(Kl + s * 64 + cg * 8);
;         const f32x2* r2 = (const f32x2*)(Rl + s * 64 + cg * 8);
;         f32x2 o[20];
; #pragma unroll
;         for (int i = 0; i < 4; ++i) { o[i] = a2[i]; o[4 + i] = w2[i]; o[8 + i] = b2[i]; o[12 + i] = k2[i]; o[16 + i] = r2[i]; }
;         const float vr = Vl[s * 64 + 32 * half + rp];
;         f32x2 p0 = St[0] * o[0], p1 = St[1] * o[1];
;         p0 = __builtin_elementwise_fma(St[2], o[2], p0); p1 = __builtin_elementwise_fma(St[3], o[3], p1);
;         const float sa = oct_sum((p0.x + p0.y) + (p1.x + p1.y));
;         const f32x2 sv = {sa, sa}, vv = {vr, vr};
;         f32x2 y0 = {0.f, 0.f}, y1 = {0.f, 0.f};
; #pragma unroll
;         for (int i = 0; i < 4; i += 2) {
;           St[i] = __builtin_elementwise_fma(St[i], o[4 + i], __builtin_elementwise_fma(sv, o[8 + i], vv * o[12 + i]));
;           St[i + 1] = __builtin_elementwise_fma(St[i + 1], o[5 + i], __builtin_elementwise_fma(sv, o[9 + i], vv * o[13 + i]));
;           y0 = __builtin_elementwise_fma(St[i], o[16 + i], y0);
;           y1 = __builtin_elementwise_fma(St[i + 1], o[17 + i], y1);
;         }
;         yy[s4] = oct_sum((y0.x + y0.y) + (y1.x + y1.y));
;       }
;       if (cg == 0) {
; #pragma unroll
;         for (int s4 = 0; s4 < 4; ++s4) Yl[(sg + s4) * 32 + rp] = yy[s4];
.LBB0_711:
	s_mov_b32 s18, -4
	v_mov_b32_e32 v0, v214
	v_mov_b32_e32 v161, v160
	v_mov_b32_e32 v162, v225
	ds_read_b128 v[34:37], v0 offset:16384
	ds_read_b128 v[38:41], v0 offset:16400
	ds_read_b128 v[68:71], v0 offset:8192
	ds_read_b128 v[150:153], v0 offset:8208
	ds_read2st64_b32 v[158:159], v161 offset0:0 offset1:1
	ds_read_b128 v[50:53], v0 offset:20480
	ds_read_b128 v[54:57], v0 offset:20496
	ds_read_b128 v[42:45], v0 offset:4096
	ds_read_b128 v[46:49], v0 offset:4112
	ds_read_b128 v[154:157], v0 offset:0
	ds_read_b128 v[246:249], v0 offset:16
	ds_read_b128 v[200:203], v0 offset:16640
	ds_read_b128 v[230:233], v0 offset:16656
	s_waitcnt lgkmcnt(11)
	v_pk_mul_f32 v[34:35], v[66:67], v[34:35]
	v_pk_mul_f32 v[36:37], v[64:65], v[36:37]
	v_pk_fma_f32 v[34:35], v[62:63], v[38:39], v[34:35]
	v_pk_fma_f32 v[36:37], v[60:61], v[40:41], v[36:37]
	v_add_f32_e32 v198, v34, v35
	v_add_f32_e32 v199, v36, v37
	v_add_f32_e32 v198, v198, v199
	s_waitcnt lgkmcnt(8)
	v_pk_mul_f32 v[58:59], v[68:69], v[158:159] op_sel_hi:[1,0]
	v_pk_mul_f32 v[72:73], v[70:71], v[158:159] op_sel_hi:[1,0]
	ds_read_b128 v[68:71], v0 offset:8448
	v_add_f32_dpp v198, v198, v198 quad_perm:[1,0,3,2] row_mask:0xf bank_mask:0xf bound_ctrl:1
	s_nop 0
	v_pk_mul_f32 v[212:213], v[150:151], v[158:159] op_sel_hi:[1,0]
	v_add_f32_dpp v198, v198, v198 quad_perm:[2,3,0,1] row_mask:0xf bank_mask:0xf bound_ctrl:1
	s_nop 0
	v_pk_mul_f32 v[250:251], v[152:153], v[158:159] op_sel_hi:[1,0]
	ds_read_b128 v[150:153], v0 offset:8464
	v_add_f32_dpp v198, v198, v198 row_half_mirror row_mask:0xf bank_mask:0xf bound_ctrl:1
	s_waitcnt lgkmcnt(8)
	v_pk_fma_f32 v[58:59], v[198:199], v[50:51], v[58:59] op_sel_hi:[0,1,1]
	v_pk_fma_f32 v[72:73], v[198:199], v[52:53], v[72:73] op_sel_hi:[0,1,1]
	s_waitcnt lgkmcnt(6)
	v_pk_fma_f32 v[66:67], v[66:67], v[42:43], v[58:59]
	v_pk_fma_f32 v[64:65], v[64:65], v[44:45], v[72:73]
	v_pk_fma_f32 v[212:213], v[198:199], v[54:55], v[212:213] op_sel_hi:[0,1,1]
	v_pk_fma_f32 v[250:251], v[198:199], v[56:57], v[250:251] op_sel_hi:[0,1,1]
	v_pk_fma_f32 v[62:63], v[62:63], v[46:47], v[212:213]
	v_pk_fma_f32 v[60:61], v[60:61], v[48:49], v[250:251]
	ds_read_b128 v[50:53], v0 offset:20736
	ds_read_b128 v[54:57], v0 offset:20752
	ds_read_b128 v[42:45], v0 offset:4352
	ds_read_b128 v[46:49], v0 offset:4368
	s_waitcnt lgkmcnt(8)
	v_pk_fma_f32 v[58:59], v[66:67], v[154:155], 0 op_sel_hi:[1,1,0]
	v_pk_fma_f32 v[72:73], v[64:65], v[156:157], 0 op_sel_hi:[1,1,0]
	v_pk_fma_f32 v[58:59], v[62:63], v[246:247], v[58:59]
	v_pk_fma_f32 v[72:73], v[60:61], v[248:249], v[72:73]
	ds_read_b128 v[154:157], v0 offset:256
	ds_read_b128 v[246:249], v0 offset:272
	v_add_f32_e32 v207, v58, v59
	v_add_f32_e32 v209, v72, v73
	ds_read_b128 v[34:37], v0 offset:16896
	ds_read_b128 v[38:41], v0 offset:16912
	s_waitcnt lgkmcnt(10)
	v_pk_mul_f32 v[200:201], v[66:67], v[200:201]
	v_pk_mul_f32 v[202:203], v[64:65], v[202:203]
	v_pk_fma_f32 v[200:201], v[62:63], v[230:231], v[200:201]
	v_pk_fma_f32 v[202:203], v[60:61], v[232:233], v[202:203]
	v_add_f32_e32 v198, v200, v201
	v_add_f32_e32 v199, v202, v203
	v_add_f32_e32 v207, v207, v209
	v_add_f32_e32 v198, v198, v199
	s_waitcnt lgkmcnt(8)
	v_pk_mul_f32 v[58:59], v[68:69], v[158:159] op_sel:[0,1] op_sel_hi:[1,1]
	v_pk_mul_f32 v[72:73], v[70:71], v[158:159] op_sel:[0,1] op_sel_hi:[1,1]
	ds_read_b128 v[68:71], v0 offset:8704
	v_add_f32_dpp v198, v198, v198 quad_perm:[1,0,3,2] row_mask:0xf bank_mask:0xf bound_ctrl:1
	v_add_f32_dpp v207, v207, v207 quad_perm:[1,0,3,2] row_mask:0xf bank_mask:0xf bound_ctrl:1
	v_pk_mul_f32 v[212:213], v[150:151], v[158:159] op_sel:[0,1] op_sel_hi:[1,1]
	v_add_f32_dpp v198, v198, v198 quad_perm:[2,3,0,1] row_mask:0xf bank_mask:0xf bound_ctrl:1
	v_add_f32_dpp v207, v207, v207 quad_perm:[2,3,0,1] row_mask:0xf bank_mask:0xf bound_ctrl:1
	v_pk_mul_f32 v[250:251], v[152:153], v[158:159] op_sel:[0,1] op_sel_hi:[1,1]
	ds_read_b128 v[150:153], v0 offset:8720
	v_add_f32_dpp v198, v198, v198 row_half_mirror row_mask:0xf bank_mask:0xf bound_ctrl:1
	v_add_f32_dpp v163, v207, v207 row_half_mirror row_mask:0xf bank_mask:0xf bound_ctrl:1
	ds_read2st64_b32 v[158:159], v161 offset0:2 offset1:3
	ds_write_b32 v162, v163 offset:0
	s_waitcnt lgkmcnt(9)
	v_pk_fma_f32 v[58:59], v[198:199], v[50:51], v[58:59] op_sel_hi:[0,1,1]
	v_pk_fma_f32 v[72:73], v[198:199], v[52:53], v[72:73] op_sel_hi:[0,1,1]
	s_waitcnt lgkmcnt(7)
	v_pk_fma_f32 v[66:67], v[66:67], v[42:43], v[58:59]
	v_pk_fma_f32 v[64:65], v[64:65], v[44:45], v[72:73]
	v_pk_fma_f32 v[212:213], v[198:199], v[54:55], v[212:213] op_sel_hi:[0,1,1]
	v_pk_fma_f32 v[250:251], v[198:199], v[56:57], v[250:251] op_sel_hi:[0,1,1]
	v_pk_fma_f32 v[62:63], v[62:63], v[46:47], v[212:213]
	v_pk_fma_f32 v[60:61], v[60:61], v[48:49], v[250:251]
	ds_read_b128 v[50:53], v0 offset:20992
	ds_read_b128 v[54:57], v0 offset:21008
	ds_read_b128 v[42:45], v0 offset:4608
	ds_read_b128 v[46:49], v0 offset:4624
	s_waitcnt lgkmcnt(9)
	v_pk_fma_f32 v[58:59], v[66:67], v[154:155], 0 op_sel_hi:[1,1,0]
	v_pk_fma_f32 v[72:73], v[64:65], v[156:157], 0 op_sel_hi:[1,1,0]
	v_pk_fma_f32 v[58:59], v[62:63], v[246:247], v[58:59]
	v_pk_fma_f32 v[72:73], v[60:61], v[248:249], v[72:73]
	ds_read_b128 v[154:157], v0 offset:512
	ds_read_b128 v[246:249], v0 offset:528
	v_add_f32_e32 v207, v58, v59
	v_add_f32_e32 v209, v72, v73
	ds_read_b128 v[200:203], v0 offset:17152
	ds_read_b128 v[230:233], v0 offset:17168
	s_waitcnt lgkmcnt(11)
	v_pk_mul_f32 v[34:35], v[66:67], v[34:35]
	v_pk_mul_f32 v[36:37], v[64:65], v[36:37]
	v_pk_fma_f32 v[34:35], v[62:63], v[38:39], v[34:35]
	v_pk_fma_f32 v[36:37], v[60:61], v[40:41], v[36:37]
	v_add_f32_e32 v198, v34, v35
	v_add_f32_e32 v199, v36, v37
	v_add_f32_e32 v207, v207, v209
	v_add_f32_e32 v198, v198, v199
	s_waitcnt lgkmcnt(8)
; DI float oct_sum(float v) { v += dpp_f<0xB1>(v); v += dpp_f<0x4E>(v); v += dpp_f<0x141>(v); return v; }
; DI void scan_item(const Params& p, int b, int h, int half, char* smem, unsigned* pgen, unsigned kp) {
;     ...
;       for (int s4 = 0; s4 < 4; ++s4) {
;         const int s = sg + s4;
;         const f32x2* a2 = (const f32x2*)(Al + s * 64 + cg * 8);
;         const f32x2* w2 = (const f32x2*)(Wl + s * 64 + cg * 8);
;         const f32x2* b2 = (const f32x2*)(Bl + s * 64 + cg * 8);
;         const f32x2* k2 = (const f32x2*)(Kl + s * 64 + cg * 8);
;         const f32x2* r2 = (const f32x2*)(Rl + s * 64 + cg * 8);
;         f32x2 o[20];
; #pragma unroll
;         for (int i = 0; i < 4; ++i) { o[i] = a2[i]; o[4 + i] = w2[i]; o[8 + i] = b2[i]; o[12 + i] = k2[i]; o[16 + i] = r2[i]; }
;         const float vr = Vl[s * 64 + 32 * half + rp];
;         f32x2 p0 = St[0] * o[0], p1 = St[1] * o[1];
;         p0 = __builtin_elementwise_fma(St[2], o[2], p0); p1 = __builtin_elementwise_fma(St[3], o[3], p1);
;         const float sa = oct_sum((p0.x + p0.y) + (p1.x + p1.y));
;         const f32x2 sv = {sa, sa}, vv = {vr, vr};
;         f32x2 y0 = {0.f, 0.f}, y1 = {0.f, 0.f};
; #pragma unroll
;         for (int i = 0; i < 4; i += 2) {
;           St[i] = __builtin_elementwise_fma(St[i], o[4 + i], __builtin_elementwise_fma(sv, o[8 + i], vv * o[12 + i]));
;           St[i + 1] = __builtin_elementwise_fma(St[i + 1], o[5 + i], __builtin_elementwise_fma(sv, o[9 + i], vv * o[13 + i]));
;           y0 = __builtin_elementwise_fma(St[i], o[16 + i], y0);
;           y1 = __builtin_elementwise_fma(St[i + 1], o[17 + i], y1);
;         }
;         yy[s4] = oct_sum((y0.x + y0.y) + (y1.x + y1.y));
;       }
;       if (cg == 0) {
; #pragma unroll
;         for (int s4 = 0; s4 < 4; ++s4) Yl[(sg + s4) * 32 + rp] = yy[s4];
	v_pk_mul_f32 v[58:59], v[68:69], v[158:159] op_sel_hi:[1,0]
	v_pk_mul_f32 v[72:73], v[70:71], v[158:159] op_sel_hi:[1,0]
	ds_read_b128 v[68:71], v0 offset:8960
	v_add_f32_dpp v198, v198, v198 quad_perm:[1,0,3,2] row_mask:0xf bank_mask:0xf bound_ctrl:1
	v_add_f32_dpp v207, v207, v207 quad_perm:[1,0,3,2] row_mask:0xf bank_mask:0xf bound_ctrl:1
	v_pk_mul_f32 v[212:213], v[150:151], v[158:159] op_sel_hi:[1,0]
	v_add_f32_dpp v198, v198, v198 quad_perm:[2,3,0,1] row_mask:0xf bank_mask:0xf bound_ctrl:1
	v_add_f32_dpp v207, v207, v207 quad_perm:[2,3,0,1] row_mask:0xf bank_mask:0xf bound_ctrl:1
	v_pk_mul_f32 v[250:251], v[152:153], v[158:159] op_sel_hi:[1,0]
	ds_read_b128 v[150:153], v0 offset:8976
	v_add_f32_dpp v198, v198, v198 row_half_mirror row_mask:0xf bank_mask:0xf bound_ctrl:1
	v_add_f32_dpp v205, v207, v207 row_half_mirror row_mask:0xf bank_mask:0xf bound_ctrl:1
	ds_write_b32 v162, v205 offset:128
	s_waitcnt lgkmcnt(8)
	v_pk_fma_f32 v[58:59], v[198:199], v[50:51], v[58:59] op_sel_hi:[0,1,1]
	v_pk_fma_f32 v[72:73], v[198:199], v[52:53], v[72:73] op_sel_hi:[0,1,1]
	s_waitcnt lgkmcnt(6)
	v_pk_fma_f32 v[66:67], v[66:67], v[42:43], v[58:59]
	v_pk_fma_f32 v[64:65], v[64:65], v[44:45], v[72:73]
	v_pk_fma_f32 v[212:213], v[198:199], v[54:55], v[212:213] op_sel_hi:[0,1,1]
	v_pk_fma_f32 v[250:251], v[198:199], v[56:57], v[250:251] op_sel_hi:[0,1,1]
	v_pk_fma_f32 v[62:63], v[62:63], v[46:47], v[212:213]
	v_pk_fma_f32 v[60:61], v[60:61], v[48:49], v[250:251]
	ds_read_b128 v[50:53], v0 offset:21248
	ds_read_b128 v[54:57], v0 offset:21264
	ds_read_b128 v[42:45], v0 offset:4864
	ds_read_b128 v[46:49], v0 offset:4880
	s_waitcnt lgkmcnt(8)
	v_pk_fma_f32 v[58:59], v[66:67], v[154:155], 0 op_sel_hi:[1,1,0]
	v_pk_fma_f32 v[72:73], v[64:65], v[156:157], 0 op_sel_hi:[1,1,0]
	v_pk_fma_f32 v[58:59], v[62:63], v[246:247], v[58:59]
	v_pk_fma_f32 v[72:73], v[60:61], v[248:249], v[72:73]
	ds_read_b128 v[154:157], v0 offset:768
	ds_read_b128 v[246:249], v0 offset:784
	v_add_f32_e32 v207, v58, v59
	v_add_f32_e32 v209, v72, v73
	ds_read_b128 v[34:37], v0 offset:17408
	ds_read_b128 v[38:41], v0 offset:17424
	s_waitcnt lgkmcnt(10)
	v_pk_mul_f32 v[200:201], v[66:67], v[200:201]
	v_pk_mul_f32 v[202:203], v[64:65], v[202:203]
	v_pk_fma_f32 v[200:201], v[62:63], v[230:231], v[200:201]
	v_pk_fma_f32 v[202:203], v[60:61], v[232:233], v[202:203]
	v_add_f32_e32 v198, v200, v201
	v_add_f32_e32 v199, v202, v203
	v_add_f32_e32 v207, v207, v209
	v_add_f32_e32 v198, v198, v199
	s_waitcnt lgkmcnt(8)
	v_pk_mul_f32 v[58:59], v[68:69], v[158:159] op_sel:[0,1] op_sel_hi:[1,1]
	v_pk_mul_f32 v[72:73], v[70:71], v[158:159] op_sel:[0,1] op_sel_hi:[1,1]
	ds_read_b128 v[68:71], v0 offset:9216
	v_add_f32_dpp v198, v198, v198 quad_perm:[1,0,3,2] row_mask:0xf bank_mask:0xf bound_ctrl:1
	v_add_f32_dpp v207, v207, v207 quad_perm:[1,0,3,2] row_mask:0xf bank_mask:0xf bound_ctrl:1
	v_pk_mul_f32 v[212:213], v[150:151], v[158:159] op_sel:[0,1] op_sel_hi:[1,1]
	v_add_f32_dpp v198, v198, v198 quad_perm:[2,3,0,1] row_mask:0xf bank_mask:0xf bound_ctrl:1
	v_add_f32_dpp v207, v207, v207 quad_perm:[2,3,0,1] row_mask:0xf bank_mask:0xf bound_ctrl:1
	v_pk_mul_f32 v[250:251], v[152:153], v[158:159] op_sel:[0,1] op_sel_hi:[1,1]
	ds_read_b128 v[150:153], v0 offset:9232
	v_add_f32_dpp v198, v198, v198 row_half_mirror row_mask:0xf bank_mask:0xf bound_ctrl:1
	v_add_f32_dpp v163, v207, v207 row_half_mirror row_mask:0xf bank_mask:0xf bound_ctrl:1
	ds_read2st64_b32 v[158:159], v161 offset0:4 offset1:5
	ds_write_b32 v162, v163 offset:256
	s_waitcnt lgkmcnt(9)
	v_pk_fma_f32 v[58:59], v[198:199], v[50:51], v[58:59] op_sel_hi:[0,1,1]
	v_pk_fma_f32 v[72:73], v[198:199], v[52:53], v[72:73] op_sel_hi:[0,1,1]
	s_waitcnt lgkmcnt(7)
	v_pk_fma_f32 v[66:67], v[66:67], v[42:43], v[58:59]
	v_pk_fma_f32 v[64:65], v[64:65], v[44:45], v[72:73]
	v_pk_fma_f32 v[212:213], v[198:199], v[54:55], v[212:213] op_sel_hi:[0,1,1]
	v_pk_fma_f32 v[250:251], v[198:199], v[56:57], v[250:251] op_sel_hi:[0,1,1]
	v_pk_fma_f32 v[62:63], v[62:63], v[46:47], v[212:213]
	v_pk_fma_f32 v[60:61], v[60:61], v[48:49], v[250:251]
	ds_read_b128 v[50:53], v0 offset:21504
	ds_read_b128 v[54:57], v0 offset:21520
	ds_read_b128 v[42:45], v0 offset:5120
	ds_read_b128 v[46:49], v0 offset:5136
	s_waitcnt lgkmcnt(9)
	v_pk_fma_f32 v[58:59], v[66:67], v[154:155], 0 op_sel_hi:[1,1,0]
	v_pk_fma_f32 v[72:73], v[64:65], v[156:157], 0 op_sel_hi:[1,1,0]
	v_pk_fma_f32 v[58:59], v[62:63], v[246:247], v[58:59]
	v_pk_fma_f32 v[72:73], v[60:61], v[248:249], v[72:73]
	ds_read_b128 v[154:157], v0 offset:1024
	ds_read_b128 v[246:249], v0 offset:1040
	v_add_f32_e32 v207, v58, v59
	v_add_f32_e32 v209, v72, v73
	ds_read_b128 v[200:203], v0 offset:17664
	ds_read_b128 v[230:233], v0 offset:17680
	s_waitcnt lgkmcnt(11)
	v_pk_mul_f32 v[34:35], v[66:67], v[34:35]
	v_pk_mul_f32 v[36:37], v[64:65], v[36:37]
	v_pk_fma_f32 v[34:35], v[62:63], v[38:39], v[34:35]
	v_pk_fma_f32 v[36:37], v[60:61], v[40:41], v[36:37]
	v_add_f32_e32 v198, v34, v35
	v_add_f32_e32 v199, v36, v37
	v_add_f32_e32 v207, v207, v209
	v_add_f32_e32 v198, v198, v199
	s_waitcnt lgkmcnt(8)
	v_pk_mul_f32 v[58:59], v[68:69], v[158:159] op_sel_hi:[1,0]
	v_pk_mul_f32 v[72:73], v[70:71], v[158:159] op_sel_hi:[1,0]
	ds_read_b128 v[68:71], v0 offset:9472
	v_add_f32_dpp v198, v198, v198 quad_perm:[1,0,3,2] row_mask:0xf bank_mask:0xf bound_ctrl:1
	v_add_f32_dpp v207, v207, v207 quad_perm:[1,0,3,2] row_mask:0xf bank_mask:0xf bound_ctrl:1
	v_pk_mul_f32 v[212:213], v[150:151], v[158:159] op_sel_hi:[1,0]
	v_add_f32_dpp v198, v198, v198 quad_perm:[2,3,0,1] row_mask:0xf bank_mask:0xf bound_ctrl:1
	v_add_f32_dpp v207, v207, v207 quad_perm:[2,3,0,1] row_mask:0xf bank_mask:0xf bound_ctrl:1
	v_pk_mul_f32 v[250:251], v[152:153], v[158:159] op_sel_hi:[1,0]
	ds_read_b128 v[150:153], v0 offset:9488
	v_add_f32_dpp v198, v198, v198 row_half_mirror row_mask:0xf bank_mask:0xf bound_ctrl:1
	v_add_f32_dpp v205, v207, v207 row_half_mirror row_mask:0xf bank_mask:0xf bound_ctrl:1
	ds_write_b32 v162, v205 offset:384
	s_waitcnt lgkmcnt(8)
; DI float oct_sum(float v) { v += dpp_f<0xB1>(v); v += dpp_f<0x4E>(v); v += dpp_f<0x141>(v); return v; }
; DI void scan_item(const Params& p, int b, int h, int half, char* smem, unsigned* pgen, unsigned kp) {
;     ...
;       for (int s4 = 0; s4 < 4; ++s4) {
;         const int s = sg + s4;
;         const f32x2* a2 = (const f32x2*)(Al + s * 64 + cg * 8);
;         const f32x2* w2 = (const f32x2*)(Wl + s * 64 + cg * 8);
;         const f32x2* b2 = (const f32x2*)(Bl + s * 64 + cg * 8);
;         const f32x2* k2 = (const f32x2*)(Kl + s * 64 + cg * 8);
;         const f32x2* r2 = (const f32x2*)(Rl + s * 64 + cg * 8);
;         f32x2 o[20];
; #pragma unroll
;         for (int i = 0; i < 4; ++i) { o[i] = a2[i]; o[4 + i] = w2[i]; o[8 + i] = b2[i]; o[12 + i] = k2[i]; o[16 + i] = r2[i]; }
;         const float vr = Vl[s * 64 + 32 * half + rp];
;         f32x2 p0 = St[0] * o[0], p1 = St[1] * o[1];
;         p0 = __builtin_elementwise_fma(St[2], o[2], p0); p1 = __builtin_elementwise_fma(St[3], o[3], p1);
;         const float sa = oct_sum((p0.x + p0.y) + (p1.x + p1.y));
;         const f32x2 sv = {sa, sa}, vv = {vr, vr};
;         f32x2 y0 = {0.f, 0.f}, y1 = {0.f, 0.f};
; #pragma unroll
;         for (int i = 0; i < 4; i += 2) {
;           St[i] = __builtin_elementwise_fma(St[i], o[4 + i], __builtin_elementwise_fma(sv, o[8 + i], vv * o[12 + i]));
;           St[i + 1] = __builtin_elementwise_fma(St[i + 1], o[5 + i], __builtin_elementwise_fma(sv, o[9 + i], vv * o[13 + i]));
;           y0 = __builtin_elementwise_fma(St[i], o[16 + i], y0);
;           y1 = __builtin_elementwise_fma(St[i + 1], o[17 + i], y1);
;         }
;         yy[s4] = oct_sum((y0.x + y0.y) + (y1.x + y1.y));
;       }
;       if (cg == 0) {
; #pragma unroll
;         for (int s4 = 0; s4 < 4; ++s4) Yl[(sg + s4) * 32 + rp] = yy[s4];
	v_pk_fma_f32 v[58:59], v[198:199], v[50:51], v[58:59] op_sel_hi:[0,1,1]
	v_pk_fma_f32 v[72:73], v[198:199], v[52:53], v[72:73] op_sel_hi:[0,1,1]
	s_waitcnt lgkmcnt(6)
	v_pk_fma_f32 v[66:67], v[66:67], v[42:43], v[58:59]
	v_pk_fma_f32 v[64:65], v[64:65], v[44:45], v[72:73]
	v_pk_fma_f32 v[212:213], v[198:199], v[54:55], v[212:213] op_sel_hi:[0,1,1]
	v_pk_fma_f32 v[250:251], v[198:199], v[56:57], v[250:251] op_sel_hi:[0,1,1]
	v_pk_fma_f32 v[62:63], v[62:63], v[46:47], v[212:213]
	v_pk_fma_f32 v[60:61], v[60:61], v[48:49], v[250:251]
	ds_read_b128 v[50:53], v0 offset:21760
	ds_read_b128 v[54:57], v0 offset:21776
	ds_read_b128 v[42:45], v0 offset:5376
	ds_read_b128 v[46:49], v0 offset:5392
	s_waitcnt lgkmcnt(8)
	v_pk_fma_f32 v[58:59], v[66:67], v[154:155], 0 op_sel_hi:[1,1,0]
	v_pk_fma_f32 v[72:73], v[64:65], v[156:157], 0 op_sel_hi:[1,1,0]
	v_pk_fma_f32 v[58:59], v[62:63], v[246:247], v[58:59]
	v_pk_fma_f32 v[72:73], v[60:61], v[248:249], v[72:73]
	ds_read_b128 v[154:157], v0 offset:1280
	ds_read_b128 v[246:249], v0 offset:1296
	v_add_f32_e32 v207, v58, v59
	v_add_f32_e32 v209, v72, v73
	ds_read_b128 v[34:37], v0 offset:17920
	ds_read_b128 v[38:41], v0 offset:17936
	s_waitcnt lgkmcnt(10)
	v_pk_mul_f32 v[200:201], v[66:67], v[200:201]
	v_pk_mul_f32 v[202:203], v[64:65], v[202:203]
	v_pk_fma_f32 v[200:201], v[62:63], v[230:231], v[200:201]
	v_pk_fma_f32 v[202:203], v[60:61], v[232:233], v[202:203]
	v_add_f32_e32 v198, v200, v201
	v_add_f32_e32 v199, v202, v203
	v_add_f32_e32 v207, v207, v209
	v_add_f32_e32 v198, v198, v199
	s_waitcnt lgkmcnt(8)
	v_pk_mul_f32 v[58:59], v[68:69], v[158:159] op_sel:[0,1] op_sel_hi:[1,1]
	v_pk_mul_f32 v[72:73], v[70:71], v[158:159] op_sel:[0,1] op_sel_hi:[1,1]
	ds_read_b128 v[68:71], v0 offset:9728
	v_add_f32_dpp v198, v198, v198 quad_perm:[1,0,3,2] row_mask:0xf bank_mask:0xf bound_ctrl:1
	v_add_f32_dpp v207, v207, v207 quad_perm:[1,0,3,2] row_mask:0xf bank_mask:0xf bound_ctrl:1
	v_pk_mul_f32 v[212:213], v[150:151], v[158:159] op_sel:[0,1] op_sel_hi:[1,1]
	v_add_f32_dpp v198, v198, v198 quad_perm:[2,3,0,1] row_mask:0xf bank_mask:0xf bound_ctrl:1
	v_add_f32_dpp v207, v207, v207 quad_perm:[2,3,0,1] row_mask:0xf bank_mask:0xf bound_ctrl:1
	v_pk_mul_f32 v[250:251], v[152:153], v[158:159] op_sel:[0,1] op_sel_hi:[1,1]
	ds_read_b128 v[150:153], v0 offset:9744
	v_add_f32_dpp v198, v198, v198 row_half_mirror row_mask:0xf bank_mask:0xf bound_ctrl:1
	v_add_f32_dpp v163, v207, v207 row_half_mirror row_mask:0xf bank_mask:0xf bound_ctrl:1
	ds_read2st64_b32 v[158:159], v161 offset0:6 offset1:7
	ds_write_b32 v162, v163 offset:512
	s_waitcnt lgkmcnt(9)
	v_pk_fma_f32 v[58:59], v[198:199], v[50:51], v[58:59] op_sel_hi:[0,1,1]
	v_pk_fma_f32 v[72:73], v[198:199], v[52:53], v[72:73] op_sel_hi:[0,1,1]
	s_waitcnt lgkmcnt(7)
	v_pk_fma_f32 v[66:67], v[66:67], v[42:43], v[58:59]
	v_pk_fma_f32 v[64:65], v[64:65], v[44:45], v[72:73]
	v_pk_fma_f32 v[212:213], v[198:199], v[54:55], v[212:213] op_sel_hi:[0,1,1]
	v_pk_fma_f32 v[250:251], v[198:199], v[56:57], v[250:251] op_sel_hi:[0,1,1]
	v_pk_fma_f32 v[62:63], v[62:63], v[46:47], v[212:213]
	v_pk_fma_f32 v[60:61], v[60:61], v[48:49], v[250:251]
	ds_read_b128 v[50:53], v0 offset:22016
	ds_read_b128 v[54:57], v0 offset:22032
	ds_read_b128 v[42:45], v0 offset:5632
	ds_read_b128 v[46:49], v0 offset:5648
	s_waitcnt lgkmcnt(9)
	v_pk_fma_f32 v[58:59], v[66:67], v[154:155], 0 op_sel_hi:[1,1,0]
	v_pk_fma_f32 v[72:73], v[64:65], v[156:157], 0 op_sel_hi:[1,1,0]
	v_pk_fma_f32 v[58:59], v[62:63], v[246:247], v[58:59]
	v_pk_fma_f32 v[72:73], v[60:61], v[248:249], v[72:73]
	ds_read_b128 v[154:157], v0 offset:1536
	ds_read_b128 v[246:249], v0 offset:1552
	v_add_f32_e32 v207, v58, v59
	v_add_f32_e32 v209, v72, v73
	ds_read_b128 v[200:203], v0 offset:18176
	ds_read_b128 v[230:233], v0 offset:18192
	s_waitcnt lgkmcnt(11)
	v_pk_mul_f32 v[34:35], v[66:67], v[34:35]
	v_pk_mul_f32 v[36:37], v[64:65], v[36:37]
	v_pk_fma_f32 v[34:35], v[62:63], v[38:39], v[34:35]
	v_pk_fma_f32 v[36:37], v[60:61], v[40:41], v[36:37]
	v_add_f32_e32 v198, v34, v35
	v_add_f32_e32 v199, v36, v37
	v_add_f32_e32 v207, v207, v209
	v_add_f32_e32 v198, v198, v199
	s_waitcnt lgkmcnt(8)
	v_pk_mul_f32 v[58:59], v[68:69], v[158:159] op_sel_hi:[1,0]
	v_pk_mul_f32 v[72:73], v[70:71], v[158:159] op_sel_hi:[1,0]
	ds_read_b128 v[68:71], v0 offset:9984
	v_add_f32_dpp v198, v198, v198 quad_perm:[1,0,3,2] row_mask:0xf bank_mask:0xf bound_ctrl:1
	v_add_f32_dpp v207, v207, v207 quad_perm:[1,0,3,2] row_mask:0xf bank_mask:0xf bound_ctrl:1
	v_pk_mul_f32 v[212:213], v[150:151], v[158:159] op_sel_hi:[1,0]
	v_add_f32_dpp v198, v198, v198 quad_perm:[2,3,0,1] row_mask:0xf bank_mask:0xf bound_ctrl:1
	v_add_f32_dpp v207, v207, v207 quad_perm:[2,3,0,1] row_mask:0xf bank_mask:0xf bound_ctrl:1
	v_pk_mul_f32 v[250:251], v[152:153], v[158:159] op_sel_hi:[1,0]
	ds_read_b128 v[150:153], v0 offset:10000
	v_add_f32_dpp v198, v198, v198 row_half_mirror row_mask:0xf bank_mask:0xf bound_ctrl:1
	v_add_f32_dpp v205, v207, v207 row_half_mirror row_mask:0xf bank_mask:0xf bound_ctrl:1
	ds_write_b32 v162, v205 offset:640
	s_waitcnt lgkmcnt(8)
	v_pk_fma_f32 v[58:59], v[198:199], v[50:51], v[58:59] op_sel_hi:[0,1,1]
	v_pk_fma_f32 v[72:73], v[198:199], v[52:53], v[72:73] op_sel_hi:[0,1,1]
	s_waitcnt lgkmcnt(6)
	v_pk_fma_f32 v[66:67], v[66:67], v[42:43], v[58:59]
	v_pk_fma_f32 v[64:65], v[64:65], v[44:45], v[72:73]
	v_pk_fma_f32 v[212:213], v[198:199], v[54:55], v[212:213] op_sel_hi:[0,1,1]
	v_pk_fma_f32 v[250:251], v[198:199], v[56:57], v[250:251] op_sel_hi:[0,1,1]
	v_pk_fma_f32 v[62:63], v[62:63], v[46:47], v[212:213]
	v_pk_fma_f32 v[60:61], v[60:61], v[48:49], v[250:251]
	ds_read_b128 v[50:53], v0 offset:22272
	ds_read_b128 v[54:57], v0 offset:22288
	ds_read_b128 v[42:45], v0 offset:5888
	ds_read_b128 v[46:49], v0 offset:5904
	s_waitcnt lgkmcnt(8)
; DI float oct_sum(float v) { v += dpp_f<0xB1>(v); v += dpp_f<0x4E>(v); v += dpp_f<0x141>(v); return v; }
; DI void scan_item(const Params& p, int b, int h, int half, char* smem, unsigned* pgen, unsigned kp) {
;     ...
;       for (int s4 = 0; s4 < 4; ++s4) {
;         const int s = sg + s4;
;         const f32x2* a2 = (const f32x2*)(Al + s * 64 + cg * 8);
;         const f32x2* w2 = (const f32x2*)(Wl + s * 64 + cg * 8);
;         const f32x2* b2 = (const f32x2*)(Bl + s * 64 + cg * 8);
;         const f32x2* k2 = (const f32x2*)(Kl + s * 64 + cg * 8);
;         const f32x2* r2 = (const f32x2*)(Rl + s * 64 + cg * 8);
;         f32x2 o[20];
; #pragma unroll
;         for (int i = 0; i < 4; ++i) { o[i] = a2[i]; o[4 + i] = w2[i]; o[8 + i] = b2[i]; o[12 + i] = k2[i]; o[16 + i] = r2[i]; }
;         const float vr = Vl[s * 64 + 32 * half + rp];
;         f32x2 p0 = St[0] * o[0], p1 = St[1] * o[1];
;         p0 = __builtin_elementwise_fma(St[2], o[2], p0); p1 = __builtin_elementwise_fma(St[3], o[3], p1);
;         const float sa = oct_sum((p0.x + p0.y) + (p1.x + p1.y));
;         const f32x2 sv = {sa, sa}, vv = {vr, vr};
;         f32x2 y0 = {0.f, 0.f}, y1 = {0.f, 0.f};
; #pragma unroll
;         for (int i = 0; i < 4; i += 2) {
;           St[i] = __builtin_elementwise_fma(St[i], o[4 + i], __builtin_elementwise_fma(sv, o[8 + i], vv * o[12 + i]));
;           St[i + 1] = __builtin_elementwise_fma(St[i + 1], o[5 + i], __builtin_elementwise_fma(sv, o[9 + i], vv * o[13 + i]));
;           y0 = __builtin_elementwise_fma(St[i], o[16 + i], y0);
;           y1 = __builtin_elementwise_fma(St[i + 1], o[17 + i], y1);
;         }
;         yy[s4] = oct_sum((y0.x + y0.y) + (y1.x + y1.y));
;       }
;       if (cg == 0) {
; #pragma unroll
;         for (int s4 = 0; s4 < 4; ++s4) Yl[(sg + s4) * 32 + rp] = yy[s4];
	v_pk_fma_f32 v[58:59], v[66:67], v[154:155], 0 op_sel_hi:[1,1,0]
	v_pk_fma_f32 v[72:73], v[64:65], v[156:157], 0 op_sel_hi:[1,1,0]
	v_pk_fma_f32 v[58:59], v[62:63], v[246:247], v[58:59]
	v_pk_fma_f32 v[72:73], v[60:61], v[248:249], v[72:73]
	ds_read_b128 v[154:157], v0 offset:1792
	ds_read_b128 v[246:249], v0 offset:1808
	v_add_f32_e32 v207, v58, v59
	v_add_f32_e32 v209, v72, v73
	ds_read_b128 v[34:37], v0 offset:18432
	ds_read_b128 v[38:41], v0 offset:18448
	s_waitcnt lgkmcnt(10)
	v_pk_mul_f32 v[200:201], v[66:67], v[200:201]
	v_pk_mul_f32 v[202:203], v[64:65], v[202:203]
	v_pk_fma_f32 v[200:201], v[62:63], v[230:231], v[200:201]
	v_pk_fma_f32 v[202:203], v[60:61], v[232:233], v[202:203]
	v_add_f32_e32 v198, v200, v201
	v_add_f32_e32 v199, v202, v203
	v_add_f32_e32 v207, v207, v209
	v_add_f32_e32 v198, v198, v199
	s_waitcnt lgkmcnt(8)
	v_pk_mul_f32 v[58:59], v[68:69], v[158:159] op_sel:[0,1] op_sel_hi:[1,1]
	v_pk_mul_f32 v[72:73], v[70:71], v[158:159] op_sel:[0,1] op_sel_hi:[1,1]
	ds_read_b128 v[68:71], v0 offset:10240
	v_add_f32_dpp v198, v198, v198 quad_perm:[1,0,3,2] row_mask:0xf bank_mask:0xf bound_ctrl:1
	v_add_f32_dpp v207, v207, v207 quad_perm:[1,0,3,2] row_mask:0xf bank_mask:0xf bound_ctrl:1
	v_pk_mul_f32 v[212:213], v[150:151], v[158:159] op_sel:[0,1] op_sel_hi:[1,1]
	v_add_f32_dpp v198, v198, v198 quad_perm:[2,3,0,1] row_mask:0xf bank_mask:0xf bound_ctrl:1
	v_add_f32_dpp v207, v207, v207 quad_perm:[2,3,0,1] row_mask:0xf bank_mask:0xf bound_ctrl:1
	v_pk_mul_f32 v[250:251], v[152:153], v[158:159] op_sel:[0,1] op_sel_hi:[1,1]
	ds_read_b128 v[150:153], v0 offset:10256
	v_add_f32_dpp v198, v198, v198 row_half_mirror row_mask:0xf bank_mask:0xf bound_ctrl:1
	v_add_f32_dpp v163, v207, v207 row_half_mirror row_mask:0xf bank_mask:0xf bound_ctrl:1
	ds_read2st64_b32 v[158:159], v161 offset0:8 offset1:9
	ds_write_b32 v162, v163 offset:768
	s_waitcnt lgkmcnt(9)
	v_pk_fma_f32 v[58:59], v[198:199], v[50:51], v[58:59] op_sel_hi:[0,1,1]
	v_pk_fma_f32 v[72:73], v[198:199], v[52:53], v[72:73] op_sel_hi:[0,1,1]
	s_waitcnt lgkmcnt(7)
	v_pk_fma_f32 v[66:67], v[66:67], v[42:43], v[58:59]
	v_pk_fma_f32 v[64:65], v[64:65], v[44:45], v[72:73]
	v_pk_fma_f32 v[212:213], v[198:199], v[54:55], v[212:213] op_sel_hi:[0,1,1]
	v_pk_fma_f32 v[250:251], v[198:199], v[56:57], v[250:251] op_sel_hi:[0,1,1]
	v_pk_fma_f32 v[62:63], v[62:63], v[46:47], v[212:213]
	v_pk_fma_f32 v[60:61], v[60:61], v[48:49], v[250:251]
	ds_read_b128 v[50:53], v0 offset:22528
	ds_read_b128 v[54:57], v0 offset:22544
	ds_read_b128 v[42:45], v0 offset:6144
	ds_read_b128 v[46:49], v0 offset:6160
	s_waitcnt lgkmcnt(9)
	v_pk_fma_f32 v[58:59], v[66:67], v[154:155], 0 op_sel_hi:[1,1,0]
	v_pk_fma_f32 v[72:73], v[64:65], v[156:157], 0 op_sel_hi:[1,1,0]
	v_pk_fma_f32 v[58:59], v[62:63], v[246:247], v[58:59]
	v_pk_fma_f32 v[72:73], v[60:61], v[248:249], v[72:73]
	ds_read_b128 v[154:157], v0 offset:2048
	ds_read_b128 v[246:249], v0 offset:2064
	v_add_f32_e32 v207, v58, v59
	v_add_f32_e32 v209, v72, v73
	ds_read_b128 v[200:203], v0 offset:18688
	ds_read_b128 v[230:233], v0 offset:18704
	s_waitcnt lgkmcnt(11)
	v_pk_mul_f32 v[34:35], v[66:67], v[34:35]
	v_pk_mul_f32 v[36:37], v[64:65], v[36:37]
	v_pk_fma_f32 v[34:35], v[62:63], v[38:39], v[34:35]
	v_pk_fma_f32 v[36:37], v[60:61], v[40:41], v[36:37]
	v_add_f32_e32 v198, v34, v35
	v_add_f32_e32 v199, v36, v37
	v_add_f32_e32 v207, v207, v209
	v_add_f32_e32 v198, v198, v199
	s_waitcnt lgkmcnt(8)
	v_pk_mul_f32 v[58:59], v[68:69], v[158:159] op_sel_hi:[1,0]
	v_pk_mul_f32 v[72:73], v[70:71], v[158:159] op_sel_hi:[1,0]
	ds_read_b128 v[68:71], v0 offset:10496
	v_add_f32_dpp v198, v198, v198 quad_perm:[1,0,3,2] row_mask:0xf bank_mask:0xf bound_ctrl:1
	v_add_f32_dpp v207, v207, v207 quad_perm:[1,0,3,2] row_mask:0xf bank_mask:0xf bound_ctrl:1
	v_pk_mul_f32 v[212:213], v[150:151], v[158:159] op_sel_hi:[1,0]
	v_add_f32_dpp v198, v198, v198 quad_perm:[2,3,0,1] row_mask:0xf bank_mask:0xf bound_ctrl:1
	v_add_f32_dpp v207, v207, v207 quad_perm:[2,3,0,1] row_mask:0xf bank_mask:0xf bound_ctrl:1
	v_pk_mul_f32 v[250:251], v[152:153], v[158:159] op_sel_hi:[1,0]
	ds_read_b128 v[150:153], v0 offset:10512
	v_add_f32_dpp v198, v198, v198 row_half_mirror row_mask:0xf bank_mask:0xf bound_ctrl:1
	v_add_f32_dpp v205, v207, v207 row_half_mirror row_mask:0xf bank_mask:0xf bound_ctrl:1
	ds_write_b32 v162, v205 offset:896
	s_waitcnt lgkmcnt(8)
	v_pk_fma_f32 v[58:59], v[198:199], v[50:51], v[58:59] op_sel_hi:[0,1,1]
	v_pk_fma_f32 v[72:73], v[198:199], v[52:53], v[72:73] op_sel_hi:[0,1,1]
	s_waitcnt lgkmcnt(6)
	v_pk_fma_f32 v[66:67], v[66:67], v[42:43], v[58:59]
	v_pk_fma_f32 v[64:65], v[64:65], v[44:45], v[72:73]
	v_pk_fma_f32 v[212:213], v[198:199], v[54:55], v[212:213] op_sel_hi:[0,1,1]
	v_pk_fma_f32 v[250:251], v[198:199], v[56:57], v[250:251] op_sel_hi:[0,1,1]
	v_pk_fma_f32 v[62:63], v[62:63], v[46:47], v[212:213]
	v_pk_fma_f32 v[60:61], v[60:61], v[48:49], v[250:251]
	ds_read_b128 v[50:53], v0 offset:22784
	ds_read_b128 v[54:57], v0 offset:22800
	ds_read_b128 v[42:45], v0 offset:6400
	ds_read_b128 v[46:49], v0 offset:6416
	s_waitcnt lgkmcnt(8)
	v_pk_fma_f32 v[58:59], v[66:67], v[154:155], 0 op_sel_hi:[1,1,0]
	v_pk_fma_f32 v[72:73], v[64:65], v[156:157], 0 op_sel_hi:[1,1,0]
	v_pk_fma_f32 v[58:59], v[62:63], v[246:247], v[58:59]
	v_pk_fma_f32 v[72:73], v[60:61], v[248:249], v[72:73]
	ds_read_b128 v[154:157], v0 offset:2304
	ds_read_b128 v[246:249], v0 offset:2320
	v_add_f32_e32 v207, v58, v59
	v_add_f32_e32 v209, v72, v73
	ds_read_b128 v[34:37], v0 offset:18944
	ds_read_b128 v[38:41], v0 offset:18960
	s_waitcnt lgkmcnt(10)
; DI float oct_sum(float v) { v += dpp_f<0xB1>(v); v += dpp_f<0x4E>(v); v += dpp_f<0x141>(v); return v; }
; DI void scan_item(const Params& p, int b, int h, int half, char* smem, unsigned* pgen, unsigned kp) {
;     ...
;       for (int s4 = 0; s4 < 4; ++s4) {
;         const int s = sg + s4;
;         const f32x2* a2 = (const f32x2*)(Al + s * 64 + cg * 8);
;         const f32x2* w2 = (const f32x2*)(Wl + s * 64 + cg * 8);
;         const f32x2* b2 = (const f32x2*)(Bl + s * 64 + cg * 8);
;         const f32x2* k2 = (const f32x2*)(Kl + s * 64 + cg * 8);
;         const f32x2* r2 = (const f32x2*)(Rl + s * 64 + cg * 8);
;         f32x2 o[20];
; #pragma unroll
;         for (int i = 0; i < 4; ++i) { o[i] = a2[i]; o[4 + i] = w2[i]; o[8 + i] = b2[i]; o[12 + i] = k2[i]; o[16 + i] = r2[i]; }
;         const float vr = Vl[s * 64 + 32 * half + rp];
;         f32x2 p0 = St[0] * o[0], p1 = St[1] * o[1];
;         p0 = __builtin_elementwise_fma(St[2], o[2], p0); p1 = __builtin_elementwise_fma(St[3], o[3], p1);
;         const float sa = oct_sum((p0.x + p0.y) + (p1.x + p1.y));
;         const f32x2 sv = {sa, sa}, vv = {vr, vr};
;         f32x2 y0 = {0.f, 0.f}, y1 = {0.f, 0.f};
; #pragma unroll
;         for (int i = 0; i < 4; i += 2) {
;           St[i] = __builtin_elementwise_fma(St[i], o[4 + i], __builtin_elementwise_fma(sv, o[8 + i], vv * o[12 + i]));
;           St[i + 1] = __builtin_elementwise_fma(St[i + 1], o[5 + i], __builtin_elementwise_fma(sv, o[9 + i], vv * o[13 + i]));
;           y0 = __builtin_elementwise_fma(St[i], o[16 + i], y0);
;           y1 = __builtin_elementwise_fma(St[i + 1], o[17 + i], y1);
;         }
;         yy[s4] = oct_sum((y0.x + y0.y) + (y1.x + y1.y));
;       }
;       if (cg == 0) {
; #pragma unroll
;         for (int s4 = 0; s4 < 4; ++s4) Yl[(sg + s4) * 32 + rp] = yy[s4];
	v_pk_mul_f32 v[200:201], v[66:67], v[200:201]
	v_pk_mul_f32 v[202:203], v[64:65], v[202:203]
	v_pk_fma_f32 v[200:201], v[62:63], v[230:231], v[200:201]
	v_pk_fma_f32 v[202:203], v[60:61], v[232:233], v[202:203]
	v_add_f32_e32 v198, v200, v201
	v_add_f32_e32 v199, v202, v203
	v_add_f32_e32 v207, v207, v209
	v_add_f32_e32 v198, v198, v199
	s_waitcnt lgkmcnt(8)
	v_pk_mul_f32 v[58:59], v[68:69], v[158:159] op_sel:[0,1] op_sel_hi:[1,1]
	v_pk_mul_f32 v[72:73], v[70:71], v[158:159] op_sel:[0,1] op_sel_hi:[1,1]
	ds_read_b128 v[68:71], v0 offset:10752
	v_add_f32_dpp v198, v198, v198 quad_perm:[1,0,3,2] row_mask:0xf bank_mask:0xf bound_ctrl:1
	v_add_f32_dpp v207, v207, v207 quad_perm:[1,0,3,2] row_mask:0xf bank_mask:0xf bound_ctrl:1
	v_pk_mul_f32 v[212:213], v[150:151], v[158:159] op_sel:[0,1] op_sel_hi:[1,1]
	v_add_f32_dpp v198, v198, v198 quad_perm:[2,3,0,1] row_mask:0xf bank_mask:0xf bound_ctrl:1
	v_add_f32_dpp v207, v207, v207 quad_perm:[2,3,0,1] row_mask:0xf bank_mask:0xf bound_ctrl:1
	v_pk_mul_f32 v[250:251], v[152:153], v[158:159] op_sel:[0,1] op_sel_hi:[1,1]
	ds_read_b128 v[150:153], v0 offset:10768
	v_add_f32_dpp v198, v198, v198 row_half_mirror row_mask:0xf bank_mask:0xf bound_ctrl:1
	v_add_f32_dpp v163, v207, v207 row_half_mirror row_mask:0xf bank_mask:0xf bound_ctrl:1
	ds_read2st64_b32 v[158:159], v161 offset0:10 offset1:11
	ds_write_b32 v162, v163 offset:1024
	s_waitcnt lgkmcnt(9)
	v_pk_fma_f32 v[58:59], v[198:199], v[50:51], v[58:59] op_sel_hi:[0,1,1]
	v_pk_fma_f32 v[72:73], v[198:199], v[52:53], v[72:73] op_sel_hi:[0,1,1]
	s_waitcnt lgkmcnt(7)
	v_pk_fma_f32 v[66:67], v[66:67], v[42:43], v[58:59]
	v_pk_fma_f32 v[64:65], v[64:65], v[44:45], v[72:73]
	v_pk_fma_f32 v[212:213], v[198:199], v[54:55], v[212:213] op_sel_hi:[0,1,1]
	v_pk_fma_f32 v[250:251], v[198:199], v[56:57], v[250:251] op_sel_hi:[0,1,1]
	v_pk_fma_f32 v[62:63], v[62:63], v[46:47], v[212:213]
	v_pk_fma_f32 v[60:61], v[60:61], v[48:49], v[250:251]
	ds_read_b128 v[50:53], v0 offset:23040
	ds_read_b128 v[54:57], v0 offset:23056
	ds_read_b128 v[42:45], v0 offset:6656
	ds_read_b128 v[46:49], v0 offset:6672
	s_waitcnt lgkmcnt(9)
	v_pk_fma_f32 v[58:59], v[66:67], v[154:155], 0 op_sel_hi:[1,1,0]
	v_pk_fma_f32 v[72:73], v[64:65], v[156:157], 0 op_sel_hi:[1,1,0]
	v_pk_fma_f32 v[58:59], v[62:63], v[246:247], v[58:59]
	v_pk_fma_f32 v[72:73], v[60:61], v[248:249], v[72:73]
	ds_read_b128 v[154:157], v0 offset:2560
	ds_read_b128 v[246:249], v0 offset:2576
	v_add_f32_e32 v207, v58, v59
	v_add_f32_e32 v209, v72, v73
	ds_read_b128 v[200:203], v0 offset:19200
	ds_read_b128 v[230:233], v0 offset:19216
	s_waitcnt lgkmcnt(11)
	v_pk_mul_f32 v[34:35], v[66:67], v[34:35]
	v_pk_mul_f32 v[36:37], v[64:65], v[36:37]
	v_pk_fma_f32 v[34:35], v[62:63], v[38:39], v[34:35]
	v_pk_fma_f32 v[36:37], v[60:61], v[40:41], v[36:37]
	v_add_f32_e32 v198, v34, v35
	v_add_f32_e32 v199, v36, v37
	v_add_f32_e32 v207, v207, v209
	v_add_f32_e32 v198, v198, v199
	s_waitcnt lgkmcnt(8)
	v_pk_mul_f32 v[58:59], v[68:69], v[158:159] op_sel_hi:[1,0]
	v_pk_mul_f32 v[72:73], v[70:71], v[158:159] op_sel_hi:[1,0]
	ds_read_b128 v[68:71], v0 offset:11008
	v_add_f32_dpp v198, v198, v198 quad_perm:[1,0,3,2] row_mask:0xf bank_mask:0xf bound_ctrl:1
	v_add_f32_dpp v207, v207, v207 quad_perm:[1,0,3,2] row_mask:0xf bank_mask:0xf bound_ctrl:1
	v_pk_mul_f32 v[212:213], v[150:151], v[158:159] op_sel_hi:[1,0]
	v_add_f32_dpp v198, v198, v198 quad_perm:[2,3,0,1] row_mask:0xf bank_mask:0xf bound_ctrl:1
	v_add_f32_dpp v207, v207, v207 quad_perm:[2,3,0,1] row_mask:0xf bank_mask:0xf bound_ctrl:1
	v_pk_mul_f32 v[250:251], v[152:153], v[158:159] op_sel_hi:[1,0]
	ds_read_b128 v[150:153], v0 offset:11024
	v_add_f32_dpp v198, v198, v198 row_half_mirror row_mask:0xf bank_mask:0xf bound_ctrl:1
	v_add_f32_dpp v205, v207, v207 row_half_mirror row_mask:0xf bank_mask:0xf bound_ctrl:1
	ds_write_b32 v162, v205 offset:1152
	s_waitcnt lgkmcnt(8)
	v_pk_fma_f32 v[58:59], v[198:199], v[50:51], v[58:59] op_sel_hi:[0,1,1]
	v_pk_fma_f32 v[72:73], v[198:199], v[52:53], v[72:73] op_sel_hi:[0,1,1]
	s_waitcnt lgkmcnt(6)
	v_pk_fma_f32 v[66:67], v[66:67], v[42:43], v[58:59]
	v_pk_fma_f32 v[64:65], v[64:65], v[44:45], v[72:73]
	v_pk_fma_f32 v[212:213], v[198:199], v[54:55], v[212:213] op_sel_hi:[0,1,1]
	v_pk_fma_f32 v[250:251], v[198:199], v[56:57], v[250:251] op_sel_hi:[0,1,1]
	v_pk_fma_f32 v[62:63], v[62:63], v[46:47], v[212:213]
	v_pk_fma_f32 v[60:61], v[60:61], v[48:49], v[250:251]
	ds_read_b128 v[50:53], v0 offset:23296
	ds_read_b128 v[54:57], v0 offset:23312
	ds_read_b128 v[42:45], v0 offset:6912
	ds_read_b128 v[46:49], v0 offset:6928
	s_waitcnt lgkmcnt(8)
	v_pk_fma_f32 v[58:59], v[66:67], v[154:155], 0 op_sel_hi:[1,1,0]
	v_pk_fma_f32 v[72:73], v[64:65], v[156:157], 0 op_sel_hi:[1,1,0]
	v_pk_fma_f32 v[58:59], v[62:63], v[246:247], v[58:59]
	v_pk_fma_f32 v[72:73], v[60:61], v[248:249], v[72:73]
	ds_read_b128 v[154:157], v0 offset:2816
	ds_read_b128 v[246:249], v0 offset:2832
	v_add_f32_e32 v207, v58, v59
	v_add_f32_e32 v209, v72, v73
	ds_read_b128 v[34:37], v0 offset:19456
	ds_read_b128 v[38:41], v0 offset:19472
	s_waitcnt lgkmcnt(10)
	v_pk_mul_f32 v[200:201], v[66:67], v[200:201]
	v_pk_mul_f32 v[202:203], v[64:65], v[202:203]
	v_pk_fma_f32 v[200:201], v[62:63], v[230:231], v[200:201]
	v_pk_fma_f32 v[202:203], v[60:61], v[232:233], v[202:203]
	v_add_f32_e32 v198, v200, v201
	v_add_f32_e32 v199, v202, v203
	v_add_f32_e32 v207, v207, v209
	v_add_f32_e32 v198, v198, v199
	s_waitcnt lgkmcnt(8)
; DI float oct_sum(float v) { v += dpp_f<0xB1>(v); v += dpp_f<0x4E>(v); v += dpp_f<0x141>(v); return v; }
; DI void scan_item(const Params& p, int b, int h, int half, char* smem, unsigned* pgen, unsigned kp) {
;     ...
;       for (int s4 = 0; s4 < 4; ++s4) {
;         const int s = sg + s4;
;         const f32x2* a2 = (const f32x2*)(Al + s * 64 + cg * 8);
;         const f32x2* w2 = (const f32x2*)(Wl + s * 64 + cg * 8);
;         const f32x2* b2 = (const f32x2*)(Bl + s * 64 + cg * 8);
;         const f32x2* k2 = (const f32x2*)(Kl + s * 64 + cg * 8);
;         const f32x2* r2 = (const f32x2*)(Rl + s * 64 + cg * 8);
;         f32x2 o[20];
; #pragma unroll
;         for (int i = 0; i < 4; ++i) { o[i] = a2[i]; o[4 + i] = w2[i]; o[8 + i] = b2[i]; o[12 + i] = k2[i]; o[16 + i] = r2[i]; }
;         const float vr = Vl[s * 64 + 32 * half + rp];
;         f32x2 p0 = St[0] * o[0], p1 = St[1] * o[1];
;         p0 = __builtin_elementwise_fma(St[2], o[2], p0); p1 = __builtin_elementwise_fma(St[3], o[3], p1);
;         const float sa = oct_sum((p0.x + p0.y) + (p1.x + p1.y));
;         const f32x2 sv = {sa, sa}, vv = {vr, vr};
;         f32x2 y0 = {0.f, 0.f}, y1 = {0.f, 0.f};
; #pragma unroll
;         for (int i = 0; i < 4; i += 2) {
;           St[i] = __builtin_elementwise_fma(St[i], o[4 + i], __builtin_elementwise_fma(sv, o[8 + i], vv * o[12 + i]));
;           St[i + 1] = __builtin_elementwise_fma(St[i + 1], o[5 + i], __builtin_elementwise_fma(sv, o[9 + i], vv * o[13 + i]));
;           y0 = __builtin_elementwise_fma(St[i], o[16 + i], y0);
;           y1 = __builtin_elementwise_fma(St[i + 1], o[17 + i], y1);
;         }
;         yy[s4] = oct_sum((y0.x + y0.y) + (y1.x + y1.y));
;       }
;       if (cg == 0) {
; #pragma unroll
;         for (int s4 = 0; s4 < 4; ++s4) Yl[(sg + s4) * 32 + rp] = yy[s4];
	v_pk_mul_f32 v[58:59], v[68:69], v[158:159] op_sel:[0,1] op_sel_hi:[1,1]
	v_pk_mul_f32 v[72:73], v[70:71], v[158:159] op_sel:[0,1] op_sel_hi:[1,1]
	ds_read_b128 v[68:71], v0 offset:11264
	v_add_f32_dpp v198, v198, v198 quad_perm:[1,0,3,2] row_mask:0xf bank_mask:0xf bound_ctrl:1
	v_add_f32_dpp v207, v207, v207 quad_perm:[1,0,3,2] row_mask:0xf bank_mask:0xf bound_ctrl:1
	v_pk_mul_f32 v[212:213], v[150:151], v[158:159] op_sel:[0,1] op_sel_hi:[1,1]
	v_add_f32_dpp v198, v198, v198 quad_perm:[2,3,0,1] row_mask:0xf bank_mask:0xf bound_ctrl:1
	v_add_f32_dpp v207, v207, v207 quad_perm:[2,3,0,1] row_mask:0xf bank_mask:0xf bound_ctrl:1
	v_pk_mul_f32 v[250:251], v[152:153], v[158:159] op_sel:[0,1] op_sel_hi:[1,1]
	ds_read_b128 v[150:153], v0 offset:11280
	v_add_f32_dpp v198, v198, v198 row_half_mirror row_mask:0xf bank_mask:0xf bound_ctrl:1
	v_add_f32_dpp v163, v207, v207 row_half_mirror row_mask:0xf bank_mask:0xf bound_ctrl:1
	ds_read2st64_b32 v[158:159], v161 offset0:12 offset1:13
	ds_write_b32 v162, v163 offset:1280
	s_waitcnt lgkmcnt(9)
	v_pk_fma_f32 v[58:59], v[198:199], v[50:51], v[58:59] op_sel_hi:[0,1,1]
	v_pk_fma_f32 v[72:73], v[198:199], v[52:53], v[72:73] op_sel_hi:[0,1,1]
	s_waitcnt lgkmcnt(7)
	v_pk_fma_f32 v[66:67], v[66:67], v[42:43], v[58:59]
	v_pk_fma_f32 v[64:65], v[64:65], v[44:45], v[72:73]
	v_pk_fma_f32 v[212:213], v[198:199], v[54:55], v[212:213] op_sel_hi:[0,1,1]
	v_pk_fma_f32 v[250:251], v[198:199], v[56:57], v[250:251] op_sel_hi:[0,1,1]
	v_pk_fma_f32 v[62:63], v[62:63], v[46:47], v[212:213]
	v_pk_fma_f32 v[60:61], v[60:61], v[48:49], v[250:251]
	ds_read_b128 v[50:53], v0 offset:23552
	ds_read_b128 v[54:57], v0 offset:23568
	ds_read_b128 v[42:45], v0 offset:7168
	ds_read_b128 v[46:49], v0 offset:7184
	s_waitcnt lgkmcnt(9)
	v_pk_fma_f32 v[58:59], v[66:67], v[154:155], 0 op_sel_hi:[1,1,0]
	v_pk_fma_f32 v[72:73], v[64:65], v[156:157], 0 op_sel_hi:[1,1,0]
	v_pk_fma_f32 v[58:59], v[62:63], v[246:247], v[58:59]
	v_pk_fma_f32 v[72:73], v[60:61], v[248:249], v[72:73]
	ds_read_b128 v[154:157], v0 offset:3072
	ds_read_b128 v[246:249], v0 offset:3088
	v_add_f32_e32 v207, v58, v59
	v_add_f32_e32 v209, v72, v73
	ds_read_b128 v[200:203], v0 offset:19712
	ds_read_b128 v[230:233], v0 offset:19728
	s_waitcnt lgkmcnt(11)
	v_pk_mul_f32 v[34:35], v[66:67], v[34:35]
	v_pk_mul_f32 v[36:37], v[64:65], v[36:37]
	v_pk_fma_f32 v[34:35], v[62:63], v[38:39], v[34:35]
	v_pk_fma_f32 v[36:37], v[60:61], v[40:41], v[36:37]
	v_add_f32_e32 v198, v34, v35
	v_add_f32_e32 v199, v36, v37
	v_add_f32_e32 v207, v207, v209
	v_add_f32_e32 v198, v198, v199
	s_waitcnt lgkmcnt(8)
	v_pk_mul_f32 v[58:59], v[68:69], v[158:159] op_sel_hi:[1,0]
	v_pk_mul_f32 v[72:73], v[70:71], v[158:159] op_sel_hi:[1,0]
	ds_read_b128 v[68:71], v0 offset:11520
	v_add_f32_dpp v198, v198, v198 quad_perm:[1,0,3,2] row_mask:0xf bank_mask:0xf bound_ctrl:1
	v_add_f32_dpp v207, v207, v207 quad_perm:[1,0,3,2] row_mask:0xf bank_mask:0xf bound_ctrl:1
	v_pk_mul_f32 v[212:213], v[150:151], v[158:159] op_sel_hi:[1,0]
	v_add_f32_dpp v198, v198, v198 quad_perm:[2,3,0,1] row_mask:0xf bank_mask:0xf bound_ctrl:1
	v_add_f32_dpp v207, v207, v207 quad_perm:[2,3,0,1] row_mask:0xf bank_mask:0xf bound_ctrl:1
	v_pk_mul_f32 v[250:251], v[152:153], v[158:159] op_sel_hi:[1,0]
	ds_read_b128 v[150:153], v0 offset:11536
	v_add_f32_dpp v198, v198, v198 row_half_mirror row_mask:0xf bank_mask:0xf bound_ctrl:1
	v_add_f32_dpp v205, v207, v207 row_half_mirror row_mask:0xf bank_mask:0xf bound_ctrl:1
	ds_write_b32 v162, v205 offset:1408
	s_waitcnt lgkmcnt(8)
	v_pk_fma_f32 v[58:59], v[198:199], v[50:51], v[58:59] op_sel_hi:[0,1,1]
	v_pk_fma_f32 v[72:73], v[198:199], v[52:53], v[72:73] op_sel_hi:[0,1,1]
	s_waitcnt lgkmcnt(6)
	v_pk_fma_f32 v[66:67], v[66:67], v[42:43], v[58:59]
	v_pk_fma_f32 v[64:65], v[64:65], v[44:45], v[72:73]
	v_pk_fma_f32 v[212:213], v[198:199], v[54:55], v[212:213] op_sel_hi:[0,1,1]
	v_pk_fma_f32 v[250:251], v[198:199], v[56:57], v[250:251] op_sel_hi:[0,1,1]
	v_pk_fma_f32 v[62:63], v[62:63], v[46:47], v[212:213]
	v_pk_fma_f32 v[60:61], v[60:61], v[48:49], v[250:251]
	ds_read_b128 v[50:53], v0 offset:23808
	ds_read_b128 v[54:57], v0 offset:23824
	ds_read_b128 v[42:45], v0 offset:7424
	ds_read_b128 v[46:49], v0 offset:7440
	s_waitcnt lgkmcnt(8)
	v_pk_fma_f32 v[58:59], v[66:67], v[154:155], 0 op_sel_hi:[1,1,0]
	v_pk_fma_f32 v[72:73], v[64:65], v[156:157], 0 op_sel_hi:[1,1,0]
	v_pk_fma_f32 v[58:59], v[62:63], v[246:247], v[58:59]
	v_pk_fma_f32 v[72:73], v[60:61], v[248:249], v[72:73]
	ds_read_b128 v[154:157], v0 offset:3328
	ds_read_b128 v[246:249], v0 offset:3344
	v_add_f32_e32 v207, v58, v59
	v_add_f32_e32 v209, v72, v73
	ds_read_b128 v[34:37], v0 offset:19968
	ds_read_b128 v[38:41], v0 offset:19984
	s_waitcnt lgkmcnt(10)
	v_pk_mul_f32 v[200:201], v[66:67], v[200:201]
	v_pk_mul_f32 v[202:203], v[64:65], v[202:203]
	v_pk_fma_f32 v[200:201], v[62:63], v[230:231], v[200:201]
	v_pk_fma_f32 v[202:203], v[60:61], v[232:233], v[202:203]
	v_add_f32_e32 v198, v200, v201
	v_add_f32_e32 v199, v202, v203
	v_add_f32_e32 v207, v207, v209
	v_add_f32_e32 v198, v198, v199
	s_waitcnt lgkmcnt(8)
	v_pk_mul_f32 v[58:59], v[68:69], v[158:159] op_sel:[0,1] op_sel_hi:[1,1]
	v_pk_mul_f32 v[72:73], v[70:71], v[158:159] op_sel:[0,1] op_sel_hi:[1,1]
	ds_read_b128 v[68:71], v0 offset:11776
	v_add_f32_dpp v198, v198, v198 quad_perm:[1,0,3,2] row_mask:0xf bank_mask:0xf bound_ctrl:1
	v_add_f32_dpp v207, v207, v207 quad_perm:[1,0,3,2] row_mask:0xf bank_mask:0xf bound_ctrl:1
	v_pk_mul_f32 v[212:213], v[150:151], v[158:159] op_sel:[0,1] op_sel_hi:[1,1]
	v_add_f32_dpp v198, v198, v198 quad_perm:[2,3,0,1] row_mask:0xf bank_mask:0xf bound_ctrl:1
	v_add_f32_dpp v207, v207, v207 quad_perm:[2,3,0,1] row_mask:0xf bank_mask:0xf bound_ctrl:1
	v_pk_mul_f32 v[250:251], v[152:153], v[158:159] op_sel:[0,1] op_sel_hi:[1,1]
	ds_read_b128 v[150:153], v0 offset:11792
	v_add_f32_dpp v198, v198, v198 row_half_mirror row_mask:0xf bank_mask:0xf bound_ctrl:1
	v_add_f32_dpp v163, v207, v207 row_half_mirror row_mask:0xf bank_mask:0xf bound_ctrl:1
	ds_read2st64_b32 v[158:159], v161 offset0:14 offset1:15
	ds_write_b32 v162, v163 offset:1536
	s_waitcnt lgkmcnt(9)
; DI float oct_sum(float v) { v += dpp_f<0xB1>(v); v += dpp_f<0x4E>(v); v += dpp_f<0x141>(v); return v; }
; DI void scan_item(const Params& p, int b, int h, int half, char* smem, unsigned* pgen, unsigned kp) {
;     ...
;       for (int s4 = 0; s4 < 4; ++s4) {
;         const int s = sg + s4;
;         const f32x2* a2 = (const f32x2*)(Al + s * 64 + cg * 8);
;         const f32x2* w2 = (const f32x2*)(Wl + s * 64 + cg * 8);
;         const f32x2* b2 = (const f32x2*)(Bl + s * 64 + cg * 8);
;         const f32x2* k2 = (const f32x2*)(Kl + s * 64 + cg * 8);
;         const f32x2* r2 = (const f32x2*)(Rl + s * 64 + cg * 8);
;         f32x2 o[20];
; #pragma unroll
;         for (int i = 0; i < 4; ++i) { o[i] = a2[i]; o[4 + i] = w2[i]; o[8 + i] = b2[i]; o[12 + i] = k2[i]; o[16 + i] = r2[i]; }
;         const float vr = Vl[s * 64 + 32 * half + rp];
;         f32x2 p0 = St[0] * o[0], p1 = St[1] * o[1];
;         p0 = __builtin_elementwise_fma(St[2], o[2], p0); p1 = __builtin_elementwise_fma(St[3], o[3], p1);
;         const float sa = oct_sum((p0.x + p0.y) + (p1.x + p1.y));
;         const f32x2 sv = {sa, sa}, vv = {vr, vr};
;         f32x2 y0 = {0.f, 0.f}, y1 = {0.f, 0.f};
; #pragma unroll
;         for (int i = 0; i < 4; i += 2) {
;           St[i] = __builtin_elementwise_fma(St[i], o[4 + i], __builtin_elementwise_fma(sv, o[8 + i], vv * o[12 + i]));
;           St[i + 1] = __builtin_elementwise_fma(St[i + 1], o[5 + i], __builtin_elementwise_fma(sv, o[9 + i], vv * o[13 + i]));
;           y0 = __builtin_elementwise_fma(St[i], o[16 + i], y0);
;           y1 = __builtin_elementwise_fma(St[i + 1], o[17 + i], y1);
;         }
;         yy[s4] = oct_sum((y0.x + y0.y) + (y1.x + y1.y));
;       }
;       if (cg == 0) {
; #pragma unroll
;         for (int s4 = 0; s4 < 4; ++s4) Yl[(sg + s4) * 32 + rp] = yy[s4];
	v_pk_fma_f32 v[58:59], v[198:199], v[50:51], v[58:59] op_sel_hi:[0,1,1]
	v_pk_fma_f32 v[72:73], v[198:199], v[52:53], v[72:73] op_sel_hi:[0,1,1]
	s_waitcnt lgkmcnt(7)
	v_pk_fma_f32 v[66:67], v[66:67], v[42:43], v[58:59]
	v_pk_fma_f32 v[64:65], v[64:65], v[44:45], v[72:73]
	v_pk_fma_f32 v[212:213], v[198:199], v[54:55], v[212:213] op_sel_hi:[0,1,1]
	v_pk_fma_f32 v[250:251], v[198:199], v[56:57], v[250:251] op_sel_hi:[0,1,1]
	v_pk_fma_f32 v[62:63], v[62:63], v[46:47], v[212:213]
	v_pk_fma_f32 v[60:61], v[60:61], v[48:49], v[250:251]
	ds_read_b128 v[50:53], v0 offset:24064
	ds_read_b128 v[54:57], v0 offset:24080
	ds_read_b128 v[42:45], v0 offset:7680
	ds_read_b128 v[46:49], v0 offset:7696
	s_waitcnt lgkmcnt(9)
	v_pk_fma_f32 v[58:59], v[66:67], v[154:155], 0 op_sel_hi:[1,1,0]
	v_pk_fma_f32 v[72:73], v[64:65], v[156:157], 0 op_sel_hi:[1,1,0]
	v_pk_fma_f32 v[58:59], v[62:63], v[246:247], v[58:59]
	v_pk_fma_f32 v[72:73], v[60:61], v[248:249], v[72:73]
	ds_read_b128 v[154:157], v0 offset:3584
	ds_read_b128 v[246:249], v0 offset:3600
	v_add_f32_e32 v207, v58, v59
	v_add_f32_e32 v209, v72, v73
	ds_read_b128 v[200:203], v0 offset:20224
	ds_read_b128 v[230:233], v0 offset:20240
	s_waitcnt lgkmcnt(11)
	v_pk_mul_f32 v[34:35], v[66:67], v[34:35]
	v_pk_mul_f32 v[36:37], v[64:65], v[36:37]
	v_pk_fma_f32 v[34:35], v[62:63], v[38:39], v[34:35]
	v_pk_fma_f32 v[36:37], v[60:61], v[40:41], v[36:37]
	v_add_f32_e32 v198, v34, v35
	v_add_f32_e32 v199, v36, v37
	v_add_f32_e32 v207, v207, v209
	v_add_f32_e32 v198, v198, v199
	s_waitcnt lgkmcnt(8)
	v_pk_mul_f32 v[58:59], v[68:69], v[158:159] op_sel_hi:[1,0]
	v_pk_mul_f32 v[72:73], v[70:71], v[158:159] op_sel_hi:[1,0]
	ds_read_b128 v[68:71], v0 offset:12032
	v_add_f32_dpp v198, v198, v198 quad_perm:[1,0,3,2] row_mask:0xf bank_mask:0xf bound_ctrl:1
	v_add_f32_dpp v207, v207, v207 quad_perm:[1,0,3,2] row_mask:0xf bank_mask:0xf bound_ctrl:1
	v_pk_mul_f32 v[212:213], v[150:151], v[158:159] op_sel_hi:[1,0]
	v_add_f32_dpp v198, v198, v198 quad_perm:[2,3,0,1] row_mask:0xf bank_mask:0xf bound_ctrl:1
	v_add_f32_dpp v207, v207, v207 quad_perm:[2,3,0,1] row_mask:0xf bank_mask:0xf bound_ctrl:1
	v_pk_mul_f32 v[250:251], v[152:153], v[158:159] op_sel_hi:[1,0]
	ds_read_b128 v[150:153], v0 offset:12048
	v_add_f32_dpp v198, v198, v198 row_half_mirror row_mask:0xf bank_mask:0xf bound_ctrl:1
	v_add_f32_dpp v205, v207, v207 row_half_mirror row_mask:0xf bank_mask:0xf bound_ctrl:1
	ds_write_b32 v162, v205 offset:1664
	s_waitcnt lgkmcnt(8)
	v_pk_fma_f32 v[58:59], v[198:199], v[50:51], v[58:59] op_sel_hi:[0,1,1]
	v_pk_fma_f32 v[72:73], v[198:199], v[52:53], v[72:73] op_sel_hi:[0,1,1]
	s_waitcnt lgkmcnt(6)
	v_pk_fma_f32 v[66:67], v[66:67], v[42:43], v[58:59]
	v_pk_fma_f32 v[64:65], v[64:65], v[44:45], v[72:73]
	v_pk_fma_f32 v[212:213], v[198:199], v[54:55], v[212:213] op_sel_hi:[0,1,1]
	v_pk_fma_f32 v[250:251], v[198:199], v[56:57], v[250:251] op_sel_hi:[0,1,1]
	v_pk_fma_f32 v[62:63], v[62:63], v[46:47], v[212:213]
	v_pk_fma_f32 v[60:61], v[60:61], v[48:49], v[250:251]
	ds_read_b128 v[50:53], v0 offset:24320
	ds_read_b128 v[54:57], v0 offset:24336
	ds_read_b128 v[42:45], v0 offset:7936
	ds_read_b128 v[46:49], v0 offset:7952
	s_waitcnt lgkmcnt(8)
	v_pk_fma_f32 v[58:59], v[66:67], v[154:155], 0 op_sel_hi:[1,1,0]
	v_pk_fma_f32 v[72:73], v[64:65], v[156:157], 0 op_sel_hi:[1,1,0]
	v_pk_fma_f32 v[58:59], v[62:63], v[246:247], v[58:59]
	v_pk_fma_f32 v[72:73], v[60:61], v[248:249], v[72:73]
	ds_read_b128 v[154:157], v0 offset:3840
	ds_read_b128 v[246:249], v0 offset:3856
	v_add_f32_e32 v207, v58, v59
	v_add_f32_e32 v209, v72, v73
	s_waitcnt lgkmcnt(8)
	v_pk_mul_f32 v[200:201], v[66:67], v[200:201]
	v_pk_mul_f32 v[202:203], v[64:65], v[202:203]
	v_pk_fma_f32 v[200:201], v[62:63], v[230:231], v[200:201]
	v_pk_fma_f32 v[202:203], v[60:61], v[232:233], v[202:203]
	v_add_f32_e32 v198, v200, v201
	v_add_f32_e32 v199, v202, v203
	v_add_f32_e32 v207, v207, v209
	v_add_f32_e32 v198, v198, v199
	s_waitcnt lgkmcnt(6)
	v_pk_mul_f32 v[58:59], v[68:69], v[158:159] op_sel:[0,1] op_sel_hi:[1,1]
	v_pk_mul_f32 v[72:73], v[70:71], v[158:159] op_sel:[0,1] op_sel_hi:[1,1]
	v_add_f32_dpp v198, v198, v198 quad_perm:[1,0,3,2] row_mask:0xf bank_mask:0xf bound_ctrl:1
	v_add_f32_dpp v207, v207, v207 quad_perm:[1,0,3,2] row_mask:0xf bank_mask:0xf bound_ctrl:1
	v_pk_mul_f32 v[212:213], v[150:151], v[158:159] op_sel:[0,1] op_sel_hi:[1,1]
	v_add_f32_dpp v198, v198, v198 quad_perm:[2,3,0,1] row_mask:0xf bank_mask:0xf bound_ctrl:1
	v_add_f32_dpp v207, v207, v207 quad_perm:[2,3,0,1] row_mask:0xf bank_mask:0xf bound_ctrl:1
	v_pk_mul_f32 v[250:251], v[152:153], v[158:159] op_sel:[0,1] op_sel_hi:[1,1]
	v_add_f32_dpp v198, v198, v198 row_half_mirror row_mask:0xf bank_mask:0xf bound_ctrl:1
	v_add_f32_dpp v163, v207, v207 row_half_mirror row_mask:0xf bank_mask:0xf bound_ctrl:1
	ds_write_b32 v162, v163 offset:1792
	s_waitcnt lgkmcnt(4)
	v_pk_fma_f32 v[58:59], v[198:199], v[50:51], v[58:59] op_sel_hi:[0,1,1]
	v_pk_fma_f32 v[72:73], v[198:199], v[52:53], v[72:73] op_sel_hi:[0,1,1]
	s_waitcnt lgkmcnt(2)
	v_pk_fma_f32 v[66:67], v[66:67], v[42:43], v[58:59]
	v_pk_fma_f32 v[64:65], v[64:65], v[44:45], v[72:73]
	v_pk_fma_f32 v[212:213], v[198:199], v[54:55], v[212:213] op_sel_hi:[0,1,1]
	v_pk_fma_f32 v[250:251], v[198:199], v[56:57], v[250:251] op_sel_hi:[0,1,1]
	v_pk_fma_f32 v[62:63], v[62:63], v[46:47], v[212:213]
	v_pk_fma_f32 v[60:61], v[60:61], v[48:49], v[250:251]
	s_waitcnt lgkmcnt(0)
	v_pk_fma_f32 v[58:59], v[66:67], v[154:155], 0 op_sel_hi:[1,1,0]
	v_pk_fma_f32 v[72:73], v[64:65], v[156:157], 0 op_sel_hi:[1,1,0]
	v_pk_fma_f32 v[58:59], v[62:63], v[246:247], v[58:59]
	v_pk_fma_f32 v[72:73], v[60:61], v[248:249], v[72:73]
	v_add_f32_e32 v207, v58, v59
	v_add_f32_e32 v209, v72, v73
	v_add_f32_e32 v207, v207, v209
	s_nop 1
	v_add_f32_dpp v207, v207, v207 quad_perm:[1,0,3,2] row_mask:0xf bank_mask:0xf bound_ctrl:1
	s_nop 1
	v_add_f32_dpp v207, v207, v207 quad_perm:[2,3,0,1] row_mask:0xf bank_mask:0xf bound_ctrl:1
	s_nop 1
	v_add_f32_dpp v205, v207, v207 row_half_mirror row_mask:0xf bank_mask:0xf bound_ctrl:1
	ds_write_b32 v162, v205 offset:1920
